# SGU-in epilogue: gelu argument chain folded from 5 to 3 VALU ops per element (x*(c1*x^2+c0), f32, same function), on top of static leading-half priority
# speedup vs baseline: 1.0077x; 1.0044x over previous
.LBB0_552:
	s_add_u32 s8, s6, 0xfffc0080
	s_addc_u32 s9, s7, -1
	s_add_i32 s35, 0, 0x10000
	s_cmp_eq_u32 s56, 12
	s_cselect_b32 s11, s4, s9
	s_cselect_b32 s10, s5, s8
	v_add_u32_e32 v140, s35, v165
	s_cselect_b32 s9, s24, s51
	s_cselect_b32 s8, s38, s47
	s_add_i32 s57, 0, 0x14000
	ds_read_b128 v[158:161], v140
	ds_read_b128 v[168:171], v140 offset:1024
	ds_read_b128 v[172:175], v140 offset:2048
	ds_read_b128 v[176:179], v140 offset:3072
	v_add_u32_e32 v140, s57, v165
	ds_read_b128 v[180:183], v140
	ds_read_b128 v[184:187], v140 offset:1024
	ds_read_b128 v[206:209], v140 offset:2048
	ds_read_b128 v[210:213], v140 offset:3072
	v_lshl_add_u64 v[142:143], s[6:7], 0, v[136:137]
	s_add_i32 m0, s66, 0xc000
	ds_read_b128 v[214:217], v166
	ds_read_b128 v[218:221], v166 offset:1024
	ds_read_b128 v[222:225], v166 offset:2048
	ds_read_b128 v[226:229], v166 offset:3072
	ds_read_b128 v[230:233], v166 offset:4096
	ds_read_b128 v[234:237], v166 offset:5120
	ds_read_b128 v[238:241], v166 offset:6144
	ds_read_b128 v[242:245], v166 offset:7168
	global_load_lds_dwordx4 v[142:143], off
	v_lshl_add_u64 v[142:143], s[6:7], 0, v[138:139]
	s_add_i32 m0, s66, 0xe000
	s_nop 0
	global_load_lds_dwordx4 v[142:143], off
	s_waitcnt vmcnt(8)
	s_waitcnt lgkmcnt(0)
	s_barrier
	v_mfma_f32_16x16x32_bf16 v[124:127], v[158:161], v[214:217], v[124:127]
	v_mfma_f32_16x16x32_bf16 v[120:123], v[172:175], v[214:217], v[120:123]
	v_mfma_f32_16x16x32_bf16 v[108:111], v[158:161], v[222:225], v[108:111]
	v_mfma_f32_16x16x32_bf16 v[104:107], v[172:175], v[222:225], v[104:107]
	v_mfma_f32_16x16x32_bf16 v[92:95], v[158:161], v[230:233], v[92:95]
	v_mfma_f32_16x16x32_bf16 v[88:91], v[172:175], v[230:233], v[88:91]
	v_mfma_f32_16x16x32_bf16 v[76:79], v[158:161], v[238:241], v[76:79]
	v_mfma_f32_16x16x32_bf16 v[72:75], v[172:175], v[238:241], v[72:75]
	v_mfma_f32_16x16x32_bf16 v[124:127], v[168:171], v[218:221], v[124:127]
	v_mfma_f32_16x16x32_bf16 v[120:123], v[176:179], v[218:221], v[120:123]
	v_mfma_f32_16x16x32_bf16 v[108:111], v[168:171], v[226:229], v[108:111]
	v_mfma_f32_16x16x32_bf16 v[104:107], v[176:179], v[226:229], v[104:107]
	v_mfma_f32_16x16x32_bf16 v[92:95], v[168:171], v[234:237], v[92:95]
	v_mfma_f32_16x16x32_bf16 v[88:91], v[176:179], v[234:237], v[88:91]
	v_mfma_f32_16x16x32_bf16 v[76:79], v[168:171], v[242:245], v[76:79]
	v_mfma_f32_16x16x32_bf16 v[72:75], v[176:179], v[242:245], v[72:75]
	v_mfma_f32_16x16x32_bf16 v[116:119], v[180:183], v[214:217], v[116:119]
	v_mfma_f32_16x16x32_bf16 v[112:115], v[206:209], v[214:217], v[112:115]
	v_mfma_f32_16x16x32_bf16 v[100:103], v[180:183], v[222:225], v[100:103]
	v_mfma_f32_16x16x32_bf16 v[96:99], v[206:209], v[222:225], v[96:99]
	v_mfma_f32_16x16x32_bf16 v[84:87], v[180:183], v[230:233], v[84:87]
	v_mfma_f32_16x16x32_bf16 v[80:83], v[206:209], v[230:233], v[80:83]
	v_mfma_f32_16x16x32_bf16 v[68:71], v[180:183], v[238:241], v[68:71]
	v_mfma_f32_16x16x32_bf16 v[64:67], v[206:209], v[238:241], v[64:67]
	v_mfma_f32_16x16x32_bf16 v[116:119], v[184:187], v[218:221], v[116:119]
	v_mfma_f32_16x16x32_bf16 v[112:115], v[210:213], v[218:221], v[112:115]
	v_mfma_f32_16x16x32_bf16 v[100:103], v[184:187], v[226:229], v[100:103]
	v_mfma_f32_16x16x32_bf16 v[96:99], v[210:213], v[226:229], v[96:99]
	v_mfma_f32_16x16x32_bf16 v[84:87], v[184:187], v[234:237], v[84:87]
	v_mfma_f32_16x16x32_bf16 v[80:83], v[210:213], v[234:237], v[80:83]
	v_mfma_f32_16x16x32_bf16 v[68:71], v[184:187], v[242:245], v[68:71]
	v_mfma_f32_16x16x32_bf16 v[64:67], v[210:213], v[242:245], v[64:67]
	s_barrier
	s_add_i32 s35, s35, s12
	v_lshl_add_u64 v[142:143], s[8:9], 0, v[132:133]
	s_mov_b32 m0, s35
	ds_read_b128 v[214:217], v166 offset:16384
	ds_read_b128 v[218:221], v166 offset:17408
	ds_read_b128 v[222:225], v166 offset:18432
	ds_read_b128 v[226:229], v166 offset:19456
	ds_read_b128 v[230:233], v166 offset:20480
	ds_read_b128 v[234:237], v166 offset:21504
	ds_read_b128 v[238:241], v166 offset:22528
	ds_read_b128 v[242:245], v166 offset:23552
	global_load_lds_dwordx4 v[142:143], off
	s_add_i32 m0, s35, 0x2000
	s_add_u32 s58, s8, 0x40000
	v_lshl_add_u64 v[144:145], s[8:9], 0, v[128:129]
	s_addc_u32 s59, s9, 0
	s_add_i32 s35, s57, s12
	global_load_lds_dwordx4 v[144:145], off
	v_lshl_add_u64 v[146:147], s[58:59], 0, v[132:133]
	s_mov_b32 m0, s35
	v_lshl_add_u64 v[148:149], s[10:11], 0, v[130:131]
	global_load_lds_dwordx4 v[146:147], off
	v_lshl_add_u64 v[146:147], s[58:59], 0, v[128:129]
	s_add_i32 m0, s35, 0x2000
	s_nop 0
	global_load_lds_dwordx4 v[146:147], off
	v_lshl_add_u64 v[146:147], s[10:11], 0, v[134:135]
	s_mov_b32 m0, s66
	s_nop 0
	global_load_lds_dwordx4 v[146:147], off
	s_mov_b32 m0, s67
	s_nop 0
	global_load_lds_dwordx4 v[148:149], off
	s_waitcnt vmcnt(8)
	s_waitcnt lgkmcnt(0)
	s_barrier
	v_mfma_f32_16x16x32_bf16 v[60:63], v[158:161], v[214:217], v[60:63]
	v_mfma_f32_16x16x32_bf16 v[56:59], v[172:175], v[214:217], v[56:59]
	v_mfma_f32_16x16x32_bf16 v[44:47], v[158:161], v[222:225], v[44:47]
	v_mfma_f32_16x16x32_bf16 v[40:43], v[172:175], v[222:225], v[40:43]
	v_mfma_f32_16x16x32_bf16 v[28:31], v[158:161], v[230:233], v[28:31]
	v_mfma_f32_16x16x32_bf16 v[24:27], v[172:175], v[230:233], v[24:27]
	v_mfma_f32_16x16x32_bf16 v[12:15], v[158:161], v[238:241], v[12:15]
	v_mfma_f32_16x16x32_bf16 v[8:11], v[172:175], v[238:241], v[8:11]
	v_mfma_f32_16x16x32_bf16 v[60:63], v[168:171], v[218:221], v[60:63]
	v_mfma_f32_16x16x32_bf16 v[56:59], v[176:179], v[218:221], v[56:59]
	v_mfma_f32_16x16x32_bf16 v[44:47], v[168:171], v[226:229], v[44:47]
	v_mfma_f32_16x16x32_bf16 v[40:43], v[176:179], v[226:229], v[40:43]
	v_mfma_f32_16x16x32_bf16 v[28:31], v[168:171], v[234:237], v[28:31]
	v_mfma_f32_16x16x32_bf16 v[24:27], v[176:179], v[234:237], v[24:27]
	v_mfma_f32_16x16x32_bf16 v[12:15], v[168:171], v[242:245], v[12:15]
	v_mfma_f32_16x16x32_bf16 v[8:11], v[176:179], v[242:245], v[8:11]
	v_mfma_f32_16x16x32_bf16 v[52:55], v[180:183], v[214:217], v[52:55]
	v_mfma_f32_16x16x32_bf16 v[48:51], v[206:209], v[214:217], v[48:51]
	v_mfma_f32_16x16x32_bf16 v[36:39], v[180:183], v[222:225], v[36:39]
	v_mfma_f32_16x16x32_bf16 v[32:35], v[206:209], v[222:225], v[32:35]
	v_mfma_f32_16x16x32_bf16 v[20:23], v[180:183], v[230:233], v[20:23]
	v_mfma_f32_16x16x32_bf16 v[16:19], v[206:209], v[230:233], v[16:19]
	v_mfma_f32_16x16x32_bf16 v[4:7], v[180:183], v[238:241], v[4:7]
	v_mfma_f32_16x16x32_bf16 v[0:3], v[206:209], v[238:241], v[0:3]
	v_mfma_f32_16x16x32_bf16 v[52:55], v[184:187], v[218:221], v[52:55]
	v_mfma_f32_16x16x32_bf16 v[48:51], v[210:213], v[218:221], v[48:51]
	v_mfma_f32_16x16x32_bf16 v[36:39], v[184:187], v[226:229], v[36:39]
	v_mfma_f32_16x16x32_bf16 v[32:35], v[210:213], v[226:229], v[32:35]
	v_mfma_f32_16x16x32_bf16 v[20:23], v[184:187], v[234:237], v[20:23]
	v_mfma_f32_16x16x32_bf16 v[16:19], v[210:213], v[234:237], v[16:19]
	v_mfma_f32_16x16x32_bf16 v[4:7], v[184:187], v[242:245], v[4:7]
	v_mfma_f32_16x16x32_bf16 v[0:3], v[210:213], v[242:245], v[0:3]
	s_barrier
	s_add_i32 s35, 0, 0x18000
	v_add_u32_e32 v140, s35, v165
	s_add_i32 s57, 0, 0x1c000
	ds_read_b128 v[158:161], v140
	ds_read_b128 v[168:171], v140 offset:1024
	ds_read_b128 v[172:175], v140 offset:2048
	ds_read_b128 v[176:179], v140 offset:3072
	v_add_u32_e32 v140, s57, v165
	ds_read_b128 v[180:183], v140
	ds_read_b128 v[184:187], v140 offset:1024
	ds_read_b128 v[206:209], v140 offset:2048
	ds_read_b128 v[210:213], v140 offset:3072
	s_add_u32 s10, s10, 0x40000
	s_addc_u32 s11, s11, 0
	s_mov_b32 m0, s74
	v_lshl_add_u64 v[150:151], s[10:11], 0, v[134:135]
	ds_read_b128 v[214:217], v166 offset:32768
	ds_read_b128 v[218:221], v166 offset:33792
	ds_read_b128 v[222:225], v166 offset:34816
	ds_read_b128 v[226:229], v166 offset:35840
	ds_read_b128 v[230:233], v166 offset:36864
	ds_read_b128 v[234:237], v166 offset:37888
	ds_read_b128 v[238:241], v166 offset:38912
	ds_read_b128 v[242:245], v166 offset:39936
	global_load_lds_dwordx4 v[150:151], off
	v_lshl_add_u64 v[150:151], s[10:11], 0, v[130:131]
	s_mov_b32 m0, s75
	s_nop 0
	global_load_lds_dwordx4 v[150:151], off
	s_waitcnt vmcnt(8)
	s_waitcnt lgkmcnt(0)
	s_barrier
	v_mfma_f32_16x16x32_bf16 v[124:127], v[158:161], v[214:217], v[124:127]
	v_mfma_f32_16x16x32_bf16 v[120:123], v[172:175], v[214:217], v[120:123]
	v_mfma_f32_16x16x32_bf16 v[108:111], v[158:161], v[222:225], v[108:111]
	v_mfma_f32_16x16x32_bf16 v[104:107], v[172:175], v[222:225], v[104:107]
	v_mfma_f32_16x16x32_bf16 v[92:95], v[158:161], v[230:233], v[92:95]
	v_mfma_f32_16x16x32_bf16 v[88:91], v[172:175], v[230:233], v[88:91]
	v_mfma_f32_16x16x32_bf16 v[76:79], v[158:161], v[238:241], v[76:79]
	v_mfma_f32_16x16x32_bf16 v[72:75], v[172:175], v[238:241], v[72:75]
	v_mfma_f32_16x16x32_bf16 v[124:127], v[168:171], v[218:221], v[124:127]
	v_mfma_f32_16x16x32_bf16 v[120:123], v[176:179], v[218:221], v[120:123]
	v_mfma_f32_16x16x32_bf16 v[108:111], v[168:171], v[226:229], v[108:111]
	v_mfma_f32_16x16x32_bf16 v[104:107], v[176:179], v[226:229], v[104:107]
	v_mfma_f32_16x16x32_bf16 v[92:95], v[168:171], v[234:237], v[92:95]
	v_mfma_f32_16x16x32_bf16 v[88:91], v[176:179], v[234:237], v[88:91]
	v_mfma_f32_16x16x32_bf16 v[76:79], v[168:171], v[242:245], v[76:79]
	v_mfma_f32_16x16x32_bf16 v[72:75], v[176:179], v[242:245], v[72:75]
	v_mfma_f32_16x16x32_bf16 v[116:119], v[180:183], v[214:217], v[116:119]
	v_mfma_f32_16x16x32_bf16 v[112:115], v[206:209], v[214:217], v[112:115]
	v_mfma_f32_16x16x32_bf16 v[100:103], v[180:183], v[222:225], v[100:103]
	v_mfma_f32_16x16x32_bf16 v[96:99], v[206:209], v[222:225], v[96:99]
	v_mfma_f32_16x16x32_bf16 v[84:87], v[180:183], v[230:233], v[84:87]
	v_mfma_f32_16x16x32_bf16 v[80:83], v[206:209], v[230:233], v[80:83]
	v_mfma_f32_16x16x32_bf16 v[68:71], v[180:183], v[238:241], v[68:71]
	v_mfma_f32_16x16x32_bf16 v[64:67], v[206:209], v[238:241], v[64:67]
	v_mfma_f32_16x16x32_bf16 v[116:119], v[184:187], v[218:221], v[116:119]
	v_mfma_f32_16x16x32_bf16 v[112:115], v[210:213], v[218:221], v[112:115]
	v_mfma_f32_16x16x32_bf16 v[100:103], v[184:187], v[226:229], v[100:103]
	v_mfma_f32_16x16x32_bf16 v[96:99], v[210:213], v[226:229], v[96:99]
	v_mfma_f32_16x16x32_bf16 v[84:87], v[184:187], v[234:237], v[84:87]
	v_mfma_f32_16x16x32_bf16 v[80:83], v[210:213], v[234:237], v[80:83]
	v_mfma_f32_16x16x32_bf16 v[68:71], v[184:187], v[242:245], v[68:71]
	v_mfma_f32_16x16x32_bf16 v[64:67], v[210:213], v[242:245], v[64:67]
	s_barrier
	s_add_i32 s10, s35, s12
	v_lshl_add_u64 v[142:143], v[142:143], 0, s[36:37]
	s_mov_b32 m0, s10
	ds_read_b128 v[214:217], v166 offset:49152
	ds_read_b128 v[218:221], v166 offset:50176
	ds_read_b128 v[222:225], v166 offset:51200
	ds_read_b128 v[226:229], v166 offset:52224
	ds_read_b128 v[230:233], v166 offset:53248
	ds_read_b128 v[234:237], v166 offset:54272
	ds_read_b128 v[238:241], v166 offset:55296
	ds_read_b128 v[242:245], v166 offset:56320
	global_load_lds_dwordx4 v[142:143], off
	s_add_i32 m0, s10, 0x2000
	s_add_u32 s8, s8, 0x40080
	v_lshl_add_u64 v[142:143], v[144:145], 0, s[36:37]
	s_addc_u32 s9, s9, 0
	s_add_i32 s10, s57, s12
	global_load_lds_dwordx4 v[142:143], off
	v_lshl_add_u64 v[142:143], s[8:9], 0, v[132:133]
	s_mov_b32 m0, s10
	s_nop 0
	global_load_lds_dwordx4 v[142:143], off
	v_lshl_add_u64 v[142:143], s[8:9], 0, v[128:129]
	s_add_i32 m0, s10, 0x2000
	s_nop 0
	global_load_lds_dwordx4 v[142:143], off
	v_lshl_add_u64 v[142:143], v[146:147], 0, s[36:37]
	s_mov_b32 m0, s26
	s_nop 0
	global_load_lds_dwordx4 v[142:143], off
	v_lshl_add_u64 v[142:143], v[148:149], 0, s[36:37]
	s_mov_b32 m0, s27
	s_nop 0
	global_load_lds_dwordx4 v[142:143], off
	s_waitcnt vmcnt(8)
	s_waitcnt lgkmcnt(0)
	s_barrier
	v_mfma_f32_16x16x32_bf16 v[60:63], v[158:161], v[214:217], v[60:63]
	v_mfma_f32_16x16x32_bf16 v[56:59], v[172:175], v[214:217], v[56:59]
	v_mfma_f32_16x16x32_bf16 v[44:47], v[158:161], v[222:225], v[44:47]
	v_mfma_f32_16x16x32_bf16 v[40:43], v[172:175], v[222:225], v[40:43]
	v_mfma_f32_16x16x32_bf16 v[28:31], v[158:161], v[230:233], v[28:31]
	v_mfma_f32_16x16x32_bf16 v[24:27], v[172:175], v[230:233], v[24:27]
	v_mfma_f32_16x16x32_bf16 v[12:15], v[158:161], v[238:241], v[12:15]
	v_mfma_f32_16x16x32_bf16 v[8:11], v[172:175], v[238:241], v[8:11]
	v_mfma_f32_16x16x32_bf16 v[60:63], v[168:171], v[218:221], v[60:63]
	v_mfma_f32_16x16x32_bf16 v[56:59], v[176:179], v[218:221], v[56:59]
	v_mfma_f32_16x16x32_bf16 v[44:47], v[168:171], v[226:229], v[44:47]
	v_mfma_f32_16x16x32_bf16 v[40:43], v[176:179], v[226:229], v[40:43]
	v_mfma_f32_16x16x32_bf16 v[28:31], v[168:171], v[234:237], v[28:31]
	v_mfma_f32_16x16x32_bf16 v[24:27], v[176:179], v[234:237], v[24:27]
	v_mfma_f32_16x16x32_bf16 v[12:15], v[168:171], v[242:245], v[12:15]
	v_mfma_f32_16x16x32_bf16 v[8:11], v[176:179], v[242:245], v[8:11]
	v_mfma_f32_16x16x32_bf16 v[52:55], v[180:183], v[214:217], v[52:55]
	v_mfma_f32_16x16x32_bf16 v[48:51], v[206:209], v[214:217], v[48:51]
	v_mfma_f32_16x16x32_bf16 v[36:39], v[180:183], v[222:225], v[36:39]
	v_mfma_f32_16x16x32_bf16 v[32:35], v[206:209], v[222:225], v[32:35]
	v_mfma_f32_16x16x32_bf16 v[20:23], v[180:183], v[230:233], v[20:23]
	v_mfma_f32_16x16x32_bf16 v[16:19], v[206:209], v[230:233], v[16:19]
	v_mfma_f32_16x16x32_bf16 v[4:7], v[180:183], v[238:241], v[4:7]
	v_mfma_f32_16x16x32_bf16 v[0:3], v[206:209], v[238:241], v[0:3]
	v_mfma_f32_16x16x32_bf16 v[52:55], v[184:187], v[218:221], v[52:55]
	v_mfma_f32_16x16x32_bf16 v[48:51], v[210:213], v[218:221], v[48:51]
	v_mfma_f32_16x16x32_bf16 v[36:39], v[184:187], v[226:229], v[36:39]
	v_mfma_f32_16x16x32_bf16 v[32:35], v[210:213], v[226:229], v[32:35]
	v_mfma_f32_16x16x32_bf16 v[20:23], v[184:187], v[234:237], v[20:23]
	v_mfma_f32_16x16x32_bf16 v[16:19], v[210:213], v[234:237], v[16:19]
	v_mfma_f32_16x16x32_bf16 v[4:7], v[184:187], v[242:245], v[4:7]
	v_mfma_f32_16x16x32_bf16 v[0:3], v[210:213], v[242:245], v[0:3]
	s_barrier
	s_add_i32 s56, s56, 2
	s_add_u32 s6, s6, 0x100
	s_addc_u32 s7, s7, 0
	s_add_u32 s47, s47, 0x100
	s_addc_u32 s51, s51, 0
	s_cmp_gt_u32 s56, 13
	s_cbranch_scc0 .LBB0_552
	v_mov_b32_e32 v152, 0xc0135761
	s_and_b64 vcc, exec, s[44:45]
	s_cbranch_vccz .LBB0_555
	s_barrier

.LBB0_559:
	s_waitcnt lgkmcnt(0)
	v_pk_mul_f32 v[120:121], v[120:121], v[164:165] op_sel_hi:[1,0]
	s_bfe_u32 s8, s4, 0x20006
	v_mul_f32_e32 v145, v121, v121
	v_fmamk_f32 v145, v145, 0xbdd2d3e7, v152
	v_mul_f32_e32 v145, v121, v145
	s_lshl_b32 s4, s95, 8
	s_lshl_b32 s5, s8, 5
	v_pk_mul_f32 v[126:127], v[126:127], v[164:165] op_sel_hi:[1,0]
	v_pk_mul_f32 v[122:123], v[122:123], v[164:165] op_sel_hi:[1,0]
	s_or_b32 s4, s5, s4
	v_exp_f32_e32 v145, v145
	v_mul_f32_e32 v147, v126, v126
	v_mul_f32_e32 v148, v122, v122
	v_lshl_or_b32 v160, v162, 3, s4
	v_lshlrev_b64 v[142:143], 12, v[158:159]
	v_fmamk_f32 v147, v147, 0xbdd2d3e7, v152
	v_fmamk_f32 v148, v148, 0xbdd2d3e7, v152
	v_ashrrev_i32_e32 v161, 31, v160
	v_lshl_add_u64 v[142:143], s[70:71], 0, v[142:143]
	v_mul_f32_e32 v147, v126, v147
	v_mul_f32_e32 v148, v122, v148
	v_cmp_eq_u32_e32 vcc, 0, v162
	v_lshl_add_u64 v[162:163], v[160:161], 1, v[142:143]
	v_pk_mul_f32 v[124:125], v[124:125], v[164:165] op_sel_hi:[1,0]
	v_mul_f32_e32 v143, v120, v120
	v_mul_f32_e32 v142, v124, v124
	v_fmamk_f32 v143, v143, 0xbdd2d3e7, v152
	v_add_f32_e32 v145, 1.0, v145
	v_fmamk_f32 v142, v142, 0xbdd2d3e7, v152
	v_mul_f32_e32 v143, v120, v143
	v_mul_f32_e32 v144, v125, v125
	v_rcp_f32_e32 v145, v145
	v_exp_f32_e32 v147, v147
	v_exp_f32_e32 v148, v148
	v_mul_f32_e32 v142, v124, v142
	v_fmamk_f32 v144, v144, 0xbdd2d3e7, v152
	v_mul_f32_e32 v144, v125, v144
	v_exp_f32_e32 v143, v143
	v_mul_f32_e32 v149, v123, v123
	v_exp_f32_e32 v142, v142
	v_mul_f32_e32 v145, v121, v145
	v_add_f32_e32 v121, 1.0, v147
	v_add_f32_e32 v147, 1.0, v148
	v_mul_f32_e32 v148, v127, v127
	v_fmamk_f32 v149, v149, 0xbdd2d3e7, v152
	v_exp_f32_e32 v144, v144
	v_fmamk_f32 v148, v148, 0xbdd2d3e7, v152
	v_mul_f32_e32 v149, v123, v149
	v_mul_f32_e32 v148, v127, v148
	v_add_f32_e32 v143, 1.0, v143
	v_add_f32_e32 v142, 1.0, v142
	v_rcp_f32_e32 v143, v143
	v_exp_f32_e32 v149, v149
	v_rcp_f32_e32 v142, v142
	v_add_f32_e32 v144, 1.0, v144
	v_exp_f32_e32 v148, v148
	v_rcp_f32_e32 v144, v144
	v_rcp_f32_e32 v147, v147
	v_rcp_f32_e32 v121, v121
	v_mul_f32_e32 v143, v120, v143
	v_add_f32_e32 v149, 1.0, v149
	v_mul_f32_e32 v146, v124, v142
	v_add_f32_e32 v148, 1.0, v148
	v_rcp_f32_e32 v149, v149
	v_fma_f32 v124, v124, v142, v143
	v_mul_f32_e32 v120, v125, v144
	v_rcp_f32_e32 v148, v148
	v_mul_f32_e32 v147, v122, v147
	v_add_f32_e32 v124, 0, v124
	v_fma_f32 v125, v125, v144, v145
	v_mul_f32_e32 v150, v126, v121
	v_mul_f32_e32 v142, v143, v143
	v_add_f32_e32 v124, v125, v124
	v_mul_f32_e32 v125, v145, v145
	v_fma_f32 v121, v126, v121, v147
	v_fmac_f32_e32 v142, v146, v146
	v_fmac_f32_e32 v125, v120, v120
	v_add_f32_e32 v121, v121, v124
	v_mul_f32_e32 v124, v147, v147
	v_mul_f32_e32 v123, v123, v149
	v_add_f32_e32 v125, v142, v125
	v_fmac_f32_e32 v124, v150, v150
	v_add_f32_e32 v124, v124, v125
	v_fma_f32 v125, v127, v148, v123
	v_mul_f32_e32 v122, v127, v148
	v_add_f32_e32 v125, v125, v121
	v_mul_f32_e32 v121, v123, v123
	v_fmac_f32_e32 v121, v122, v122
	v_add_f32_e32 v124, v121, v124
	v_cvt_pk_bf16_f32 v120, v146, v120
	v_cvt_pk_bf16_f32 v121, v150, v122
	v_cvt_pk_bf16_f32 v122, v143, v145
	v_cvt_pk_bf16_f32 v123, v147, v123
	v_pk_mul_f32 v[112:113], v[112:113], v[164:165] op_sel_hi:[1,0]
	global_store_dwordx4 v[162:163], v[120:123], off nt
	v_pk_mul_f32 v[118:119], v[118:119], v[164:165] op_sel_hi:[1,0]
	v_pk_mul_f32 v[114:115], v[114:115], v[164:165] op_sel_hi:[1,0]
	v_mul_f32_e32 v123, v113, v113
	v_fmamk_f32 v123, v123, 0xbdd2d3e7, v152
	v_mul_f32_e32 v123, v113, v123
	v_exp_f32_e32 v123, v123
	v_mul_f32_e32 v127, v118, v118
	v_mul_f32_e32 v142, v114, v114
	v_fmamk_f32 v127, v127, 0xbdd2d3e7, v152
	v_fmamk_f32 v142, v142, 0xbdd2d3e7, v152
	v_mul_f32_e32 v127, v118, v127
	v_mul_f32_e32 v142, v114, v142
	v_pk_mul_f32 v[116:117], v[116:117], v[164:165] op_sel_hi:[1,0]
	v_mul_f32_e32 v121, v112, v112
	v_mul_f32_e32 v120, v116, v116
	v_fmamk_f32 v121, v121, 0xbdd2d3e7, v152
	v_add_f32_e32 v123, 1.0, v123
	v_fmamk_f32 v120, v120, 0xbdd2d3e7, v152
	v_mul_f32_e32 v121, v112, v121
	v_mul_f32_e32 v122, v117, v117
	v_rcp_f32_e32 v123, v123
	v_exp_f32_e32 v127, v127
	v_exp_f32_e32 v142, v142
	v_mul_f32_e32 v120, v116, v120
	v_fmamk_f32 v122, v122, 0xbdd2d3e7, v152
	v_mul_f32_e32 v122, v117, v122
	v_exp_f32_e32 v121, v121
	v_mul_f32_e32 v143, v115, v115
	v_exp_f32_e32 v120, v120
	v_mul_f32_e32 v113, v113, v123
	v_add_f32_e32 v123, 1.0, v127
	v_add_f32_e32 v127, 1.0, v142
	v_mul_f32_e32 v142, v119, v119
	v_fmamk_f32 v143, v143, 0xbdd2d3e7, v152
	v_exp_f32_e32 v122, v122
	v_fmamk_f32 v142, v142, 0xbdd2d3e7, v152
	v_mul_f32_e32 v143, v115, v143
	v_mul_f32_e32 v142, v119, v142
	v_add_f32_e32 v121, 1.0, v121
	v_add_f32_e32 v120, 1.0, v120
	v_rcp_f32_e32 v121, v121
	v_exp_f32_e32 v143, v143
	v_rcp_f32_e32 v120, v120
	v_add_f32_e32 v122, 1.0, v122
	v_exp_f32_e32 v142, v142
	v_rcp_f32_e32 v122, v122
	v_rcp_f32_e32 v127, v127
	v_rcp_f32_e32 v123, v123
	v_mul_f32_e32 v112, v112, v121
	v_add_f32_e32 v143, 1.0, v143
	v_mul_f32_e32 v126, v116, v120
	v_add_f32_e32 v142, 1.0, v142
	v_rcp_f32_e32 v143, v143
	v_fma_f32 v116, v116, v120, v112
	v_mul_f32_e32 v121, v117, v122
	v_rcp_f32_e32 v142, v142
	v_mul_f32_e32 v114, v114, v127
	v_add_f32_e32 v116, v116, v125
	v_mul_f32_e32 v120, v112, v112
	v_fma_f32 v117, v117, v122, v113
	v_mul_f32_e32 v144, v118, v123
	v_fmac_f32_e32 v120, v126, v126
	v_add_f32_e32 v116, v117, v116
	v_mul_f32_e32 v117, v113, v113
	v_fma_f32 v118, v118, v123, v114
	v_add_f32_e32 v120, v120, v124
	v_fmac_f32_e32 v117, v121, v121
	v_add_f32_e32 v116, v118, v116
	v_mul_f32_e32 v118, v114, v114
	v_mul_f32_e32 v115, v115, v143
	v_add_f32_e32 v117, v117, v120
	v_fmac_f32_e32 v118, v144, v144
	v_add_f32_e32 v117, v118, v117
	v_fma_f32 v118, v119, v142, v115
	v_mul_f32_e32 v127, v119, v142
	v_add_f32_e32 v120, v118, v116
	v_mul_f32_e32 v116, v115, v115
	v_fmac_f32_e32 v116, v127, v127
	v_add_f32_e32 v122, v116, v117
	v_cvt_pk_bf16_f32 v116, v126, v121
	v_mov_b32_e32 v121, v120
	s_nop 1
	v_permlane16_swap_b32_e32 v121, v120
	v_mov_b32_e32 v123, v122
	s_nop 1
	v_permlane16_swap_b32_e32 v123, v122
	v_cvt_pk_bf16_f32 v117, v144, v127
	v_cvt_pk_bf16_f32 v118, v112, v113
	v_cvt_pk_bf16_f32 v119, v114, v115
	s_waitcnt lgkmcnt(0)
	v_add_f32_e32 v112, v120, v121
	v_add_f32_e32 v114, v122, v123
	v_mov_b32_e32 v113, v112
	s_nop 1
	v_permlane32_swap_b32_e32 v113, v112
	v_mov_b32_e32 v115, v114
	s_nop 1
	v_permlane32_swap_b32_e32 v115, v114
	s_cmp_gt_i32 s95, 3
	s_cselect_b64 s[4:5], -1, 0
	s_and_b64 s[58:59], s[4:5], vcc
	global_store_dwordx4 v[162:163], v[116:119], off offset:256 nt
	s_and_saveexec_b64 s[6:7], s[58:59]
	s_cbranch_execz .LBB0_561
	s_waitcnt lgkmcnt(0)
	v_add_f32_e32 v114, v114, v115
	v_add_f32_e32 v115, v112, v113
	s_lshl_b32 s4, s95, 2
	v_lshlrev_b64 v[112:113], 7, v[158:159]
	s_add_i32 s38, s4, -16
	v_lshl_add_u64 v[112:113], s[72:73], 0, v[112:113]
	v_lshl_add_u64 v[112:113], s[38:39], 2, v[112:113]
	s_lshl_b32 s38, s8, 2
	v_lshl_add_u64 v[112:113], v[112:113], 0, s[38:39]
	global_store_dword v[112:113], v115, off
	global_store_dword v[112:113], v114, off offset:64

.LBB0_565:
	s_waitcnt lgkmcnt(0)
	v_pk_mul_f32 v[108:109], v[108:109], v[116:117] op_sel_hi:[1,0]
	v_lshlrev_b64 v[114:115], 12, v[112:113]
	v_mul_f32_e32 v117, v108, v108
	v_fmamk_f32 v117, v117, 0xbdd2d3e7, v152
	v_mul_f32_e32 v117, v108, v117
	v_exp_f32_e32 v117, v117
	v_mul_f32_e32 v119, v109, v109
	v_fmamk_f32 v119, v119, 0xbdd2d3e7, v152
	v_mul_f32_e32 v119, v109, v119
	v_pk_mul_f32 v[104:105], v[104:105], v[116:117] op_sel_hi:[1,0]
	v_pk_mul_f32 v[110:111], v[110:111], v[116:117] op_sel_hi:[1,0]
	v_mul_f32_e32 v120, v105, v105
	v_fmamk_f32 v120, v120, 0xbdd2d3e7, v152
	v_mul_f32_e32 v120, v105, v120
	v_pk_mul_f32 v[106:107], v[106:107], v[116:117] op_sel_hi:[1,0]
	v_exp_f32_e32 v120, v120
	v_mul_f32_e32 v122, v110, v110
	v_mul_f32_e32 v123, v106, v106
	v_fmamk_f32 v122, v122, 0xbdd2d3e7, v152
	v_fmamk_f32 v123, v123, 0xbdd2d3e7, v152
	v_mul_f32_e32 v118, v104, v104
	v_mul_f32_e32 v122, v110, v122
	v_mul_f32_e32 v123, v106, v123
	v_fmamk_f32 v118, v118, 0xbdd2d3e7, v152
	v_mul_f32_e32 v118, v104, v118
	v_add_f32_e32 v120, 1.0, v120
	v_rcp_f32_e32 v120, v120
	v_exp_f32_e32 v122, v122
	v_exp_f32_e32 v123, v123
	v_exp_f32_e32 v118, v118
	v_mul_f32_e32 v124, v107, v107
	v_exp_f32_e32 v119, v119
	v_mul_f32_e32 v120, v105, v120
	v_add_f32_e32 v105, 1.0, v122
	v_add_f32_e32 v122, 1.0, v123
	v_mul_f32_e32 v123, v111, v111
	v_fmamk_f32 v124, v124, 0xbdd2d3e7, v152
	v_fmamk_f32 v123, v123, 0xbdd2d3e7, v152
	v_mul_f32_e32 v124, v107, v124
	v_add_f32_e32 v118, 1.0, v118
	v_mul_f32_e32 v123, v111, v123
	v_add_f32_e32 v117, 1.0, v117
	v_rcp_f32_e32 v118, v118
	v_rcp_f32_e32 v117, v117
	v_add_f32_e32 v119, 1.0, v119
	v_exp_f32_e32 v124, v124
	v_rcp_f32_e32 v119, v119
	v_exp_f32_e32 v123, v123
	v_rcp_f32_e32 v122, v122
	v_mul_f32_e32 v118, v104, v118
	v_rcp_f32_e32 v105, v105
	v_mul_f32_e32 v121, v108, v117
	v_add_f32_e32 v124, 1.0, v124
	v_fma_f32 v108, v108, v117, v118
	v_mul_f32_e32 v104, v109, v119
	v_add_f32_e32 v123, 1.0, v123
	v_rcp_f32_e32 v124, v124
	v_add_f32_e32 v108, 0, v108
	v_mul_f32_e32 v117, v118, v118
	v_fma_f32 v109, v109, v119, v120
	v_rcp_f32_e32 v123, v123
	v_mul_f32_e32 v122, v106, v122
	v_fmac_f32_e32 v117, v121, v121
	v_add_f32_e32 v108, v109, v108
	v_mul_f32_e32 v109, v120, v120
	v_mul_f32_e32 v125, v110, v105
	v_fmac_f32_e32 v109, v104, v104
	v_fma_f32 v105, v110, v105, v122
	v_pk_mul_f32 v[96:97], v[96:97], v[116:117] op_sel_hi:[1,0]
	v_add_f32_e32 v109, v117, v109
	v_add_f32_e32 v105, v105, v108
	v_mul_f32_e32 v108, v122, v122
	v_pk_mul_f32 v[100:101], v[100:101], v[116:117] op_sel_hi:[1,0]
	v_pk_mul_f32 v[102:103], v[102:103], v[116:117] op_sel_hi:[1,0]
	v_pk_mul_f32 v[98:99], v[98:99], v[116:117] op_sel_hi:[1,0]
	v_mul_f32_e32 v117, v97, v97
	v_mul_f32_e32 v107, v107, v124
	v_fmac_f32_e32 v108, v125, v125
	v_fmamk_f32 v117, v117, 0xbdd2d3e7, v152
	v_add_f32_e32 v108, v108, v109
	v_fma_f32 v109, v111, v123, v107
	v_mul_f32_e32 v117, v97, v117
	v_mul_f32_e32 v106, v111, v123
	v_add_f32_e32 v109, v109, v105
	v_mul_f32_e32 v105, v107, v107
	v_fmac_f32_e32 v105, v106, v106
	v_add_f32_e32 v108, v105, v108
	v_cvt_pk_bf16_f32 v104, v121, v104
	v_cvt_pk_bf16_f32 v105, v125, v106
	v_cvt_pk_bf16_f32 v106, v118, v120
	v_exp_f32_e32 v117, v117
	v_mul_f32_e32 v119, v102, v102
	v_mul_f32_e32 v120, v98, v98
	v_fmamk_f32 v119, v119, 0xbdd2d3e7, v152
	v_fmamk_f32 v120, v120, 0xbdd2d3e7, v152
	v_mul_f32_e32 v119, v102, v119
	v_mul_f32_e32 v120, v98, v120
	v_mul_f32_e32 v111, v96, v96
	v_mul_f32_e32 v110, v100, v100
	v_fmamk_f32 v111, v111, 0xbdd2d3e7, v152
	v_add_f32_e32 v117, 1.0, v117
	v_fmamk_f32 v110, v110, 0xbdd2d3e7, v152
	v_mul_f32_e32 v111, v96, v111
	v_mul_f32_e32 v116, v101, v101
	v_rcp_f32_e32 v117, v117
	v_exp_f32_e32 v119, v119
	v_exp_f32_e32 v120, v120
	v_mul_f32_e32 v121, v99, v99
	v_mul_f32_e32 v110, v100, v110
	v_fmamk_f32 v116, v116, 0xbdd2d3e7, v152
	v_fmamk_f32 v121, v121, 0xbdd2d3e7, v152
	v_mul_f32_e32 v116, v101, v116
	v_mul_f32_e32 v121, v99, v121
	v_exp_f32_e32 v111, v111
	v_exp_f32_e32 v110, v110
	v_mul_f32_e32 v117, v97, v117
	v_add_f32_e32 v97, 1.0, v119
	v_add_f32_e32 v119, 1.0, v120
	v_mul_f32_e32 v120, v103, v103
	v_exp_f32_e32 v116, v116
	v_fmamk_f32 v120, v120, 0xbdd2d3e7, v152
	v_exp_f32_e32 v121, v121
	v_mul_f32_e32 v120, v103, v120
	v_add_f32_e32 v111, 1.0, v111
	v_add_f32_e32 v110, 1.0, v110
	v_rcp_f32_e32 v111, v111
	v_rcp_f32_e32 v110, v110
	v_add_f32_e32 v116, 1.0, v116
	v_exp_f32_e32 v120, v120
	v_rcp_f32_e32 v119, v119
	v_add_f32_e32 v121, 1.0, v121
	v_rcp_f32_e32 v116, v116
	v_rcp_f32_e32 v121, v121
	v_rcp_f32_e32 v97, v97
	v_mul_f32_e32 v111, v96, v111
	v_add_f32_e32 v120, 1.0, v120
	v_mul_f32_e32 v119, v98, v119
	v_fma_f32 v98, v100, v110, v111
	v_mul_f32_e32 v118, v100, v110
	v_rcp_f32_e32 v120, v120
	v_mul_f32_e32 v121, v99, v121
	v_add_f32_e32 v98, v98, v109
	v_mul_f32_e32 v99, v111, v111
	v_fma_f32 v100, v101, v116, v117
	v_cvt_pk_bf16_f32 v107, v122, v107
	v_mul_f32_e32 v96, v101, v116
	v_mul_f32_e32 v122, v102, v97
	v_fmac_f32_e32 v99, v118, v118
	v_add_f32_e32 v98, v100, v98
	v_mul_f32_e32 v100, v117, v117
	v_fma_f32 v97, v102, v97, v119
	v_add_f32_e32 v99, v99, v108
	v_fmac_f32_e32 v100, v96, v96
	v_add_f32_e32 v97, v97, v98
	v_mul_f32_e32 v98, v119, v119
	v_add_f32_e32 v99, v100, v99
	v_fmac_f32_e32 v98, v122, v122
	v_add_f32_e32 v98, v98, v99
	v_fma_f32 v99, v103, v120, v121
	v_mul_f32_e32 v123, v103, v120
	v_add_f32_e32 v97, v99, v97
	v_mul_f32_e32 v99, v121, v121
	v_fmac_f32_e32 v99, v123, v123
	v_add_f32_e32 v98, v99, v98
	v_mov_b32_e32 v101, v97
	s_nop 1
	v_permlane16_swap_b32_e32 v101, v97
	v_mov_b32_e32 v99, v98
	s_nop 1
	v_permlane16_swap_b32_e32 v99, v98
	v_lshl_add_u64 v[114:115], s[70:71], 0, v[114:115]
	v_lshl_add_u64 v[114:115], v[160:161], 1, v[114:115]
	global_store_dwordx4 v[114:115], v[104:107], off nt
	v_cvt_pk_bf16_f32 v100, v118, v96
	s_waitcnt lgkmcnt(0)
	v_add_f32_e32 v96, v97, v101
	v_add_f32_e32 v98, v98, v99
	v_mov_b32_e32 v97, v96
	s_nop 1
	v_permlane32_swap_b32_e32 v97, v96
	v_mov_b32_e32 v99, v98
	s_nop 1
	v_permlane32_swap_b32_e32 v99, v98
	v_cvt_pk_bf16_f32 v101, v122, v123
	v_cvt_pk_bf16_f32 v102, v111, v117
	v_cvt_pk_bf16_f32 v103, v119, v121
	global_store_dwordx4 v[114:115], v[100:103], off offset:256 nt
	s_and_saveexec_b64 s[6:7], s[58:59]
	s_cbranch_execz .LBB0_567
	s_waitcnt lgkmcnt(0)
	v_add_f32_e32 v98, v98, v99
	v_add_f32_e32 v99, v96, v97
	s_lshl_b32 s4, s95, 2
	v_lshlrev_b64 v[96:97], 7, v[112:113]
	s_add_i32 s38, s4, -16
	v_lshl_add_u64 v[96:97], s[72:73], 0, v[96:97]
	v_lshl_add_u64 v[96:97], s[38:39], 2, v[96:97]
	s_lshl_b32 s38, s8, 2
	v_lshl_add_u64 v[96:97], v[96:97], 0, s[38:39]
	global_store_dword v[96:97], v99, off
	global_store_dword v[96:97], v98, off offset:64

.LBB0_571:
	s_waitcnt lgkmcnt(0)
	v_pk_mul_f32 v[92:93], v[92:93], v[100:101] op_sel_hi:[1,0]
	v_lshlrev_b64 v[98:99], 12, v[96:97]
	v_mul_f32_e32 v101, v92, v92
	v_fmamk_f32 v101, v101, 0xbdd2d3e7, v152
	v_mul_f32_e32 v101, v92, v101
	v_exp_f32_e32 v101, v101
	v_mul_f32_e32 v103, v93, v93
	v_fmamk_f32 v103, v103, 0xbdd2d3e7, v152
	v_mul_f32_e32 v103, v93, v103
	v_pk_mul_f32 v[88:89], v[88:89], v[100:101] op_sel_hi:[1,0]
	v_pk_mul_f32 v[94:95], v[94:95], v[100:101] op_sel_hi:[1,0]
	v_mul_f32_e32 v104, v89, v89
	v_fmamk_f32 v104, v104, 0xbdd2d3e7, v152
	v_mul_f32_e32 v104, v89, v104
	v_pk_mul_f32 v[90:91], v[90:91], v[100:101] op_sel_hi:[1,0]
	v_exp_f32_e32 v104, v104
	v_mul_f32_e32 v106, v94, v94
	v_mul_f32_e32 v107, v90, v90
	v_fmamk_f32 v106, v106, 0xbdd2d3e7, v152
	v_fmamk_f32 v107, v107, 0xbdd2d3e7, v152
	v_mul_f32_e32 v102, v88, v88
	v_mul_f32_e32 v106, v94, v106
	v_mul_f32_e32 v107, v90, v107
	v_fmamk_f32 v102, v102, 0xbdd2d3e7, v152
	v_mul_f32_e32 v102, v88, v102
	v_add_f32_e32 v104, 1.0, v104
	v_rcp_f32_e32 v104, v104
	v_exp_f32_e32 v106, v106
	v_exp_f32_e32 v107, v107
	v_exp_f32_e32 v102, v102
	v_mul_f32_e32 v108, v91, v91
	v_exp_f32_e32 v103, v103
	v_mul_f32_e32 v104, v89, v104
	v_add_f32_e32 v89, 1.0, v106
	v_add_f32_e32 v106, 1.0, v107
	v_mul_f32_e32 v107, v95, v95
	v_fmamk_f32 v108, v108, 0xbdd2d3e7, v152
	v_fmamk_f32 v107, v107, 0xbdd2d3e7, v152
	v_mul_f32_e32 v108, v91, v108
	v_add_f32_e32 v102, 1.0, v102
	v_mul_f32_e32 v107, v95, v107
	v_add_f32_e32 v101, 1.0, v101
	v_rcp_f32_e32 v102, v102
	v_rcp_f32_e32 v101, v101
	v_add_f32_e32 v103, 1.0, v103
	v_exp_f32_e32 v108, v108
	v_rcp_f32_e32 v103, v103
	v_exp_f32_e32 v107, v107
	v_rcp_f32_e32 v106, v106
	v_mul_f32_e32 v102, v88, v102
	v_rcp_f32_e32 v89, v89
	v_mul_f32_e32 v105, v92, v101
	v_add_f32_e32 v108, 1.0, v108
	v_fma_f32 v92, v92, v101, v102
	v_mul_f32_e32 v88, v93, v103
	v_add_f32_e32 v107, 1.0, v107
	v_rcp_f32_e32 v108, v108
	v_add_f32_e32 v92, 0, v92
	v_mul_f32_e32 v101, v102, v102
	v_fma_f32 v93, v93, v103, v104
	v_rcp_f32_e32 v107, v107
	v_mul_f32_e32 v106, v90, v106
	v_fmac_f32_e32 v101, v105, v105
	v_add_f32_e32 v92, v93, v92
	v_mul_f32_e32 v93, v104, v104
	v_mul_f32_e32 v109, v94, v89
	v_fmac_f32_e32 v93, v88, v88
	v_fma_f32 v89, v94, v89, v106
	v_pk_mul_f32 v[80:81], v[80:81], v[100:101] op_sel_hi:[1,0]
	v_add_f32_e32 v93, v101, v93
	v_add_f32_e32 v89, v89, v92
	v_mul_f32_e32 v92, v106, v106
	v_pk_mul_f32 v[84:85], v[84:85], v[100:101] op_sel_hi:[1,0]
	v_pk_mul_f32 v[86:87], v[86:87], v[100:101] op_sel_hi:[1,0]
	v_pk_mul_f32 v[82:83], v[82:83], v[100:101] op_sel_hi:[1,0]
	v_mul_f32_e32 v101, v81, v81
	v_mul_f32_e32 v91, v91, v108
	v_fmac_f32_e32 v92, v109, v109
	v_fmamk_f32 v101, v101, 0xbdd2d3e7, v152
	v_add_f32_e32 v92, v92, v93
	v_fma_f32 v93, v95, v107, v91
	v_mul_f32_e32 v101, v81, v101
	v_mul_f32_e32 v90, v95, v107
	v_add_f32_e32 v93, v93, v89
	v_mul_f32_e32 v89, v91, v91
	v_fmac_f32_e32 v89, v90, v90
	v_add_f32_e32 v92, v89, v92
	v_cvt_pk_bf16_f32 v88, v105, v88
	v_cvt_pk_bf16_f32 v89, v109, v90
	v_cvt_pk_bf16_f32 v90, v102, v104
	v_exp_f32_e32 v101, v101
	v_mul_f32_e32 v103, v86, v86
	v_mul_f32_e32 v104, v82, v82
	v_fmamk_f32 v103, v103, 0xbdd2d3e7, v152
	v_fmamk_f32 v104, v104, 0xbdd2d3e7, v152
	v_mul_f32_e32 v103, v86, v103
	v_mul_f32_e32 v104, v82, v104
	v_mul_f32_e32 v95, v80, v80
	v_mul_f32_e32 v94, v84, v84
	v_fmamk_f32 v95, v95, 0xbdd2d3e7, v152
	v_add_f32_e32 v101, 1.0, v101
	v_fmamk_f32 v94, v94, 0xbdd2d3e7, v152
	v_mul_f32_e32 v95, v80, v95
	v_mul_f32_e32 v100, v85, v85
	v_rcp_f32_e32 v101, v101
	v_exp_f32_e32 v103, v103
	v_exp_f32_e32 v104, v104
	v_mul_f32_e32 v105, v83, v83
	v_mul_f32_e32 v94, v84, v94
	v_fmamk_f32 v100, v100, 0xbdd2d3e7, v152
	v_fmamk_f32 v105, v105, 0xbdd2d3e7, v152
	v_mul_f32_e32 v100, v85, v100
	v_mul_f32_e32 v105, v83, v105
	v_exp_f32_e32 v95, v95
	v_exp_f32_e32 v94, v94
	v_mul_f32_e32 v101, v81, v101
	v_add_f32_e32 v81, 1.0, v103
	v_add_f32_e32 v103, 1.0, v104
	v_mul_f32_e32 v104, v87, v87
	v_exp_f32_e32 v100, v100
	v_fmamk_f32 v104, v104, 0xbdd2d3e7, v152
	v_exp_f32_e32 v105, v105
	v_mul_f32_e32 v104, v87, v104
	v_add_f32_e32 v95, 1.0, v95
	v_add_f32_e32 v94, 1.0, v94
	v_rcp_f32_e32 v95, v95
	v_rcp_f32_e32 v94, v94
	v_add_f32_e32 v100, 1.0, v100
	v_exp_f32_e32 v104, v104
	v_rcp_f32_e32 v103, v103
	v_add_f32_e32 v105, 1.0, v105
	v_rcp_f32_e32 v100, v100
	v_rcp_f32_e32 v105, v105
	v_rcp_f32_e32 v81, v81
	v_mul_f32_e32 v95, v80, v95
	v_add_f32_e32 v104, 1.0, v104
	v_mul_f32_e32 v103, v82, v103
	v_fma_f32 v82, v84, v94, v95
	v_mul_f32_e32 v102, v84, v94
	v_rcp_f32_e32 v104, v104
	v_mul_f32_e32 v105, v83, v105
	v_add_f32_e32 v82, v82, v93
	v_mul_f32_e32 v83, v95, v95
	v_fma_f32 v84, v85, v100, v101
	v_cvt_pk_bf16_f32 v91, v106, v91
	v_mul_f32_e32 v80, v85, v100
	v_mul_f32_e32 v106, v86, v81
	v_fmac_f32_e32 v83, v102, v102
	v_add_f32_e32 v82, v84, v82
	v_mul_f32_e32 v84, v101, v101
	v_fma_f32 v81, v86, v81, v103
	v_add_f32_e32 v83, v83, v92
	v_fmac_f32_e32 v84, v80, v80
	v_add_f32_e32 v81, v81, v82
	v_mul_f32_e32 v82, v103, v103
	v_add_f32_e32 v83, v84, v83
	v_fmac_f32_e32 v82, v106, v106
	v_add_f32_e32 v82, v82, v83
	v_fma_f32 v83, v87, v104, v105
	v_mul_f32_e32 v107, v87, v104
	v_add_f32_e32 v81, v83, v81
	v_mul_f32_e32 v83, v105, v105
	v_fmac_f32_e32 v83, v107, v107
	v_add_f32_e32 v82, v83, v82
	v_mov_b32_e32 v85, v81
	s_nop 1
	v_permlane16_swap_b32_e32 v85, v81
	v_mov_b32_e32 v83, v82
	s_nop 1
	v_permlane16_swap_b32_e32 v83, v82
	v_lshl_add_u64 v[98:99], s[70:71], 0, v[98:99]
	v_lshl_add_u64 v[98:99], v[160:161], 1, v[98:99]
	global_store_dwordx4 v[98:99], v[88:91], off nt
	v_cvt_pk_bf16_f32 v84, v102, v80
	s_waitcnt lgkmcnt(0)
	v_add_f32_e32 v80, v81, v85
	v_add_f32_e32 v82, v82, v83
	v_mov_b32_e32 v81, v80
	s_nop 1
	v_permlane32_swap_b32_e32 v81, v80
	v_mov_b32_e32 v83, v82
	s_nop 1
	v_permlane32_swap_b32_e32 v83, v82
	v_cvt_pk_bf16_f32 v85, v106, v107
	v_cvt_pk_bf16_f32 v86, v95, v101
	v_cvt_pk_bf16_f32 v87, v103, v105
	global_store_dwordx4 v[98:99], v[84:87], off offset:256 nt
	s_and_saveexec_b64 s[6:7], s[58:59]
	s_cbranch_execz .LBB0_573
	s_waitcnt lgkmcnt(0)
	v_add_f32_e32 v82, v82, v83
	v_add_f32_e32 v83, v80, v81
	s_lshl_b32 s4, s95, 2
	v_lshlrev_b64 v[80:81], 7, v[96:97]
	s_add_i32 s38, s4, -16
	v_lshl_add_u64 v[80:81], s[72:73], 0, v[80:81]
	v_lshl_add_u64 v[80:81], s[38:39], 2, v[80:81]
	s_lshl_b32 s38, s8, 2
	v_lshl_add_u64 v[80:81], v[80:81], 0, s[38:39]
	global_store_dword v[80:81], v83, off
	global_store_dword v[80:81], v82, off offset:64

.LBB0_577:
	s_waitcnt lgkmcnt(0)
	v_pk_mul_f32 v[76:77], v[76:77], v[84:85] op_sel_hi:[1,0]
	v_lshlrev_b64 v[82:83], 12, v[80:81]
	v_mul_f32_e32 v85, v76, v76
	v_fmamk_f32 v85, v85, 0xbdd2d3e7, v152
	v_mul_f32_e32 v85, v76, v85
	v_exp_f32_e32 v85, v85
	v_mul_f32_e32 v87, v77, v77
	v_fmamk_f32 v87, v87, 0xbdd2d3e7, v152
	v_mul_f32_e32 v87, v77, v87
	v_pk_mul_f32 v[72:73], v[72:73], v[84:85] op_sel_hi:[1,0]
	v_pk_mul_f32 v[78:79], v[78:79], v[84:85] op_sel_hi:[1,0]
	v_mul_f32_e32 v88, v73, v73
	v_fmamk_f32 v88, v88, 0xbdd2d3e7, v152
	v_mul_f32_e32 v88, v73, v88
	v_pk_mul_f32 v[74:75], v[74:75], v[84:85] op_sel_hi:[1,0]
	v_exp_f32_e32 v88, v88
	v_mul_f32_e32 v90, v78, v78
	v_mul_f32_e32 v91, v74, v74
	v_fmamk_f32 v90, v90, 0xbdd2d3e7, v152
	v_fmamk_f32 v91, v91, 0xbdd2d3e7, v152
	v_mul_f32_e32 v86, v72, v72
	v_mul_f32_e32 v90, v78, v90
	v_mul_f32_e32 v91, v74, v91
	v_fmamk_f32 v86, v86, 0xbdd2d3e7, v152
	v_mul_f32_e32 v86, v72, v86
	v_add_f32_e32 v88, 1.0, v88
	v_rcp_f32_e32 v88, v88
	v_exp_f32_e32 v90, v90
	v_exp_f32_e32 v91, v91
	v_exp_f32_e32 v86, v86
	v_mul_f32_e32 v92, v75, v75
	v_exp_f32_e32 v87, v87
	v_mul_f32_e32 v88, v73, v88
	v_add_f32_e32 v73, 1.0, v90
	v_add_f32_e32 v90, 1.0, v91
	v_mul_f32_e32 v91, v79, v79
	v_fmamk_f32 v92, v92, 0xbdd2d3e7, v152
	v_fmamk_f32 v91, v91, 0xbdd2d3e7, v152
	v_mul_f32_e32 v92, v75, v92
	v_add_f32_e32 v86, 1.0, v86
	v_mul_f32_e32 v91, v79, v91
	v_add_f32_e32 v85, 1.0, v85
	v_rcp_f32_e32 v86, v86
	v_rcp_f32_e32 v85, v85
	v_add_f32_e32 v87, 1.0, v87
	v_exp_f32_e32 v92, v92
	v_rcp_f32_e32 v87, v87
	v_exp_f32_e32 v91, v91
	v_rcp_f32_e32 v90, v90
	v_mul_f32_e32 v86, v72, v86
	v_rcp_f32_e32 v73, v73
	v_mul_f32_e32 v89, v76, v85
	v_add_f32_e32 v92, 1.0, v92
	v_fma_f32 v76, v76, v85, v86
	v_mul_f32_e32 v72, v77, v87
	v_add_f32_e32 v91, 1.0, v91
	v_rcp_f32_e32 v92, v92
	v_add_f32_e32 v76, 0, v76
	v_mul_f32_e32 v85, v86, v86
	v_fma_f32 v77, v77, v87, v88
	v_rcp_f32_e32 v91, v91
	v_mul_f32_e32 v90, v74, v90
	v_fmac_f32_e32 v85, v89, v89
	v_add_f32_e32 v76, v77, v76
	v_mul_f32_e32 v77, v88, v88
	v_mul_f32_e32 v93, v78, v73
	v_fmac_f32_e32 v77, v72, v72
	v_fma_f32 v73, v78, v73, v90
	v_pk_mul_f32 v[64:65], v[64:65], v[84:85] op_sel_hi:[1,0]
	v_add_f32_e32 v77, v85, v77
	v_add_f32_e32 v73, v73, v76
	v_mul_f32_e32 v76, v90, v90
	v_pk_mul_f32 v[68:69], v[68:69], v[84:85] op_sel_hi:[1,0]
	v_pk_mul_f32 v[70:71], v[70:71], v[84:85] op_sel_hi:[1,0]
	v_pk_mul_f32 v[66:67], v[66:67], v[84:85] op_sel_hi:[1,0]
	v_mul_f32_e32 v85, v65, v65
	v_mul_f32_e32 v75, v75, v92
	v_fmac_f32_e32 v76, v93, v93
	v_fmamk_f32 v85, v85, 0xbdd2d3e7, v152
	v_add_f32_e32 v76, v76, v77
	v_fma_f32 v77, v79, v91, v75
	v_mul_f32_e32 v85, v65, v85
	v_mul_f32_e32 v74, v79, v91
	v_add_f32_e32 v77, v77, v73
	v_mul_f32_e32 v73, v75, v75
	v_fmac_f32_e32 v73, v74, v74
	v_add_f32_e32 v76, v73, v76
	v_cvt_pk_bf16_f32 v72, v89, v72
	v_cvt_pk_bf16_f32 v73, v93, v74
	v_cvt_pk_bf16_f32 v74, v86, v88
	v_exp_f32_e32 v85, v85
	v_mul_f32_e32 v87, v70, v70
	v_mul_f32_e32 v88, v66, v66
	v_fmamk_f32 v87, v87, 0xbdd2d3e7, v152
	v_fmamk_f32 v88, v88, 0xbdd2d3e7, v152
	v_mul_f32_e32 v87, v70, v87
	v_mul_f32_e32 v88, v66, v88
	v_mul_f32_e32 v79, v64, v64
	v_mul_f32_e32 v78, v68, v68
	v_fmamk_f32 v79, v79, 0xbdd2d3e7, v152
	v_add_f32_e32 v85, 1.0, v85
	v_fmamk_f32 v78, v78, 0xbdd2d3e7, v152
	v_mul_f32_e32 v79, v64, v79
	v_mul_f32_e32 v84, v69, v69
	v_rcp_f32_e32 v85, v85
	v_exp_f32_e32 v87, v87
	v_exp_f32_e32 v88, v88
	v_mul_f32_e32 v89, v67, v67
	v_mul_f32_e32 v78, v68, v78
	v_fmamk_f32 v84, v84, 0xbdd2d3e7, v152
	v_fmamk_f32 v89, v89, 0xbdd2d3e7, v152
	v_mul_f32_e32 v84, v69, v84
	v_mul_f32_e32 v89, v67, v89
	v_exp_f32_e32 v79, v79
	v_exp_f32_e32 v78, v78
	v_mul_f32_e32 v85, v65, v85
	v_add_f32_e32 v65, 1.0, v87
	v_add_f32_e32 v87, 1.0, v88
	v_mul_f32_e32 v88, v71, v71
	v_exp_f32_e32 v84, v84
	v_fmamk_f32 v88, v88, 0xbdd2d3e7, v152
	v_exp_f32_e32 v89, v89
	v_mul_f32_e32 v88, v71, v88
	v_add_f32_e32 v79, 1.0, v79
	v_add_f32_e32 v78, 1.0, v78
	v_rcp_f32_e32 v79, v79
	v_rcp_f32_e32 v78, v78
	v_add_f32_e32 v84, 1.0, v84
	v_exp_f32_e32 v88, v88
	v_rcp_f32_e32 v87, v87
	v_add_f32_e32 v89, 1.0, v89
	v_rcp_f32_e32 v84, v84
	v_rcp_f32_e32 v89, v89
	v_rcp_f32_e32 v65, v65
	v_mul_f32_e32 v79, v64, v79
	v_add_f32_e32 v88, 1.0, v88
	v_mul_f32_e32 v87, v66, v87
	v_fma_f32 v66, v68, v78, v79
	v_mul_f32_e32 v86, v68, v78
	v_rcp_f32_e32 v88, v88
	v_mul_f32_e32 v89, v67, v89
	v_add_f32_e32 v66, v66, v77
	v_mul_f32_e32 v67, v79, v79
	v_fma_f32 v68, v69, v84, v85
	v_cvt_pk_bf16_f32 v75, v90, v75
	v_mul_f32_e32 v64, v69, v84
	v_mul_f32_e32 v90, v70, v65
	v_fmac_f32_e32 v67, v86, v86
	v_add_f32_e32 v66, v68, v66
	v_mul_f32_e32 v68, v85, v85
	v_fma_f32 v65, v70, v65, v87
	v_add_f32_e32 v67, v67, v76
	v_fmac_f32_e32 v68, v64, v64
	v_add_f32_e32 v65, v65, v66
	v_mul_f32_e32 v66, v87, v87
	v_add_f32_e32 v67, v68, v67
	v_fmac_f32_e32 v66, v90, v90
	v_add_f32_e32 v66, v66, v67
	v_fma_f32 v67, v71, v88, v89
	v_mul_f32_e32 v91, v71, v88
	v_add_f32_e32 v65, v67, v65
	v_mul_f32_e32 v67, v89, v89
	v_fmac_f32_e32 v67, v91, v91
	v_add_f32_e32 v66, v67, v66
	v_mov_b32_e32 v69, v65
	s_nop 1
	v_permlane16_swap_b32_e32 v69, v65
	v_mov_b32_e32 v67, v66
	s_nop 1
	v_permlane16_swap_b32_e32 v67, v66
	v_lshl_add_u64 v[82:83], s[70:71], 0, v[82:83]
	v_lshl_add_u64 v[82:83], v[160:161], 1, v[82:83]
	global_store_dwordx4 v[82:83], v[72:75], off nt
	v_cvt_pk_bf16_f32 v68, v86, v64
	s_waitcnt lgkmcnt(0)
	v_add_f32_e32 v64, v65, v69
	v_add_f32_e32 v66, v66, v67
	v_mov_b32_e32 v65, v64
	s_nop 1
	v_permlane32_swap_b32_e32 v65, v64
	v_mov_b32_e32 v67, v66
	s_nop 1
	v_permlane32_swap_b32_e32 v67, v66
	v_cvt_pk_bf16_f32 v69, v90, v91
	v_cvt_pk_bf16_f32 v70, v79, v85
	v_cvt_pk_bf16_f32 v71, v87, v89
	global_store_dwordx4 v[82:83], v[68:71], off offset:256 nt
	s_and_saveexec_b64 s[6:7], s[58:59]
	s_cbranch_execz .LBB0_579
	s_waitcnt lgkmcnt(0)
	v_add_f32_e32 v66, v66, v67
	v_add_f32_e32 v67, v64, v65
	s_lshl_b32 s4, s95, 2
	v_lshlrev_b64 v[64:65], 7, v[80:81]
	s_add_i32 s38, s4, -16
	v_lshl_add_u64 v[64:65], s[72:73], 0, v[64:65]
	v_lshl_add_u64 v[64:65], s[38:39], 2, v[64:65]
	s_lshl_b32 s38, s8, 2
	v_lshl_add_u64 v[64:65], v[64:65], 0, s[38:39]
	global_store_dword v[64:65], v67, off
	global_store_dword v[64:65], v66, off offset:64

.LBB0_583:
	s_waitcnt lgkmcnt(0)
	v_pk_mul_f32 v[60:61], v[60:61], v[68:69] op_sel_hi:[1,0]
	v_lshlrev_b64 v[66:67], 12, v[64:65]
	v_mul_f32_e32 v69, v60, v60
	v_fmamk_f32 v69, v69, 0xbdd2d3e7, v152
	v_mul_f32_e32 v69, v60, v69
	v_exp_f32_e32 v69, v69
	v_mul_f32_e32 v71, v61, v61
	v_fmamk_f32 v71, v71, 0xbdd2d3e7, v152
	v_mul_f32_e32 v71, v61, v71
	v_pk_mul_f32 v[56:57], v[56:57], v[68:69] op_sel_hi:[1,0]
	v_pk_mul_f32 v[62:63], v[62:63], v[68:69] op_sel_hi:[1,0]
	v_mul_f32_e32 v72, v57, v57
	v_fmamk_f32 v72, v72, 0xbdd2d3e7, v152
	v_mul_f32_e32 v72, v57, v72
	v_pk_mul_f32 v[58:59], v[58:59], v[68:69] op_sel_hi:[1,0]
	v_exp_f32_e32 v72, v72
	v_mul_f32_e32 v74, v62, v62
	v_mul_f32_e32 v75, v58, v58
	v_fmamk_f32 v74, v74, 0xbdd2d3e7, v152
	v_fmamk_f32 v75, v75, 0xbdd2d3e7, v152
	v_mul_f32_e32 v70, v56, v56
	v_mul_f32_e32 v74, v62, v74
	v_mul_f32_e32 v75, v58, v75
	v_fmamk_f32 v70, v70, 0xbdd2d3e7, v152
	v_mul_f32_e32 v70, v56, v70
	v_add_f32_e32 v72, 1.0, v72
	v_rcp_f32_e32 v72, v72
	v_exp_f32_e32 v74, v74
	v_exp_f32_e32 v75, v75
	v_exp_f32_e32 v70, v70
	v_mul_f32_e32 v76, v59, v59
	v_exp_f32_e32 v71, v71
	v_mul_f32_e32 v72, v57, v72
	v_add_f32_e32 v57, 1.0, v74
	v_add_f32_e32 v74, 1.0, v75
	v_mul_f32_e32 v75, v63, v63
	v_fmamk_f32 v76, v76, 0xbdd2d3e7, v152
	v_fmamk_f32 v75, v75, 0xbdd2d3e7, v152
	v_mul_f32_e32 v76, v59, v76
	v_add_f32_e32 v70, 1.0, v70
	v_mul_f32_e32 v75, v63, v75
	v_add_f32_e32 v69, 1.0, v69
	v_rcp_f32_e32 v70, v70
	v_rcp_f32_e32 v69, v69
	v_add_f32_e32 v71, 1.0, v71
	v_exp_f32_e32 v76, v76
	v_rcp_f32_e32 v71, v71
	v_exp_f32_e32 v75, v75
	v_rcp_f32_e32 v74, v74
	v_mul_f32_e32 v70, v56, v70
	v_rcp_f32_e32 v57, v57
	v_mul_f32_e32 v73, v60, v69
	v_add_f32_e32 v76, 1.0, v76
	v_fma_f32 v60, v60, v69, v70
	v_mul_f32_e32 v56, v61, v71
	v_add_f32_e32 v75, 1.0, v75
	v_rcp_f32_e32 v76, v76
	v_add_f32_e32 v60, 0, v60
	v_mul_f32_e32 v69, v70, v70
	v_fma_f32 v61, v61, v71, v72
	v_rcp_f32_e32 v75, v75
	v_mul_f32_e32 v74, v58, v74
	v_fmac_f32_e32 v69, v73, v73
	v_add_f32_e32 v60, v61, v60
	v_mul_f32_e32 v61, v72, v72
	v_mul_f32_e32 v77, v62, v57
	v_fmac_f32_e32 v61, v56, v56
	v_fma_f32 v57, v62, v57, v74
	v_pk_mul_f32 v[48:49], v[48:49], v[68:69] op_sel_hi:[1,0]
	v_add_f32_e32 v61, v69, v61
	v_add_f32_e32 v57, v57, v60
	v_mul_f32_e32 v60, v74, v74
	v_pk_mul_f32 v[52:53], v[52:53], v[68:69] op_sel_hi:[1,0]
	v_pk_mul_f32 v[54:55], v[54:55], v[68:69] op_sel_hi:[1,0]
	v_pk_mul_f32 v[50:51], v[50:51], v[68:69] op_sel_hi:[1,0]
	v_mul_f32_e32 v69, v49, v49
	v_mul_f32_e32 v59, v59, v76
	v_fmac_f32_e32 v60, v77, v77
	v_fmamk_f32 v69, v69, 0xbdd2d3e7, v152
	v_add_f32_e32 v60, v60, v61
	v_fma_f32 v61, v63, v75, v59
	v_mul_f32_e32 v69, v49, v69
	v_mul_f32_e32 v58, v63, v75
	v_add_f32_e32 v61, v61, v57
	v_mul_f32_e32 v57, v59, v59
	v_fmac_f32_e32 v57, v58, v58
	v_add_f32_e32 v60, v57, v60
	v_cvt_pk_bf16_f32 v56, v73, v56
	v_cvt_pk_bf16_f32 v57, v77, v58
	v_cvt_pk_bf16_f32 v58, v70, v72
	v_exp_f32_e32 v69, v69
	v_mul_f32_e32 v71, v54, v54
	v_mul_f32_e32 v72, v50, v50
	v_fmamk_f32 v71, v71, 0xbdd2d3e7, v152
	v_fmamk_f32 v72, v72, 0xbdd2d3e7, v152
	v_mul_f32_e32 v71, v54, v71
	v_mul_f32_e32 v72, v50, v72
	v_mul_f32_e32 v63, v48, v48
	v_mul_f32_e32 v62, v52, v52
	v_fmamk_f32 v63, v63, 0xbdd2d3e7, v152
	v_add_f32_e32 v69, 1.0, v69
	v_fmamk_f32 v62, v62, 0xbdd2d3e7, v152
	v_mul_f32_e32 v63, v48, v63
	v_mul_f32_e32 v68, v53, v53
	v_rcp_f32_e32 v69, v69
	v_exp_f32_e32 v71, v71
	v_exp_f32_e32 v72, v72
	v_mul_f32_e32 v73, v51, v51
	v_mul_f32_e32 v62, v52, v62
	v_fmamk_f32 v68, v68, 0xbdd2d3e7, v152
	v_fmamk_f32 v73, v73, 0xbdd2d3e7, v152
	v_mul_f32_e32 v68, v53, v68
	v_mul_f32_e32 v73, v51, v73
	v_exp_f32_e32 v63, v63
	v_exp_f32_e32 v62, v62
	v_mul_f32_e32 v69, v49, v69
	v_add_f32_e32 v49, 1.0, v71
	v_add_f32_e32 v71, 1.0, v72
	v_mul_f32_e32 v72, v55, v55
	v_exp_f32_e32 v68, v68
	v_fmamk_f32 v72, v72, 0xbdd2d3e7, v152
	v_exp_f32_e32 v73, v73
	v_mul_f32_e32 v72, v55, v72
	v_add_f32_e32 v63, 1.0, v63
	v_add_f32_e32 v62, 1.0, v62
	v_rcp_f32_e32 v63, v63
	v_rcp_f32_e32 v62, v62
	v_add_f32_e32 v68, 1.0, v68
	v_exp_f32_e32 v72, v72
	v_rcp_f32_e32 v71, v71
	v_add_f32_e32 v73, 1.0, v73
	v_rcp_f32_e32 v68, v68
	v_rcp_f32_e32 v73, v73
	v_rcp_f32_e32 v49, v49
	v_mul_f32_e32 v63, v48, v63
	v_add_f32_e32 v72, 1.0, v72
	v_mul_f32_e32 v71, v50, v71
	v_fma_f32 v50, v52, v62, v63
	v_mul_f32_e32 v70, v52, v62
	v_rcp_f32_e32 v72, v72
	v_mul_f32_e32 v73, v51, v73
	v_add_f32_e32 v50, v50, v61
	v_mul_f32_e32 v51, v63, v63
	v_fma_f32 v52, v53, v68, v69
	v_cvt_pk_bf16_f32 v59, v74, v59
	v_mul_f32_e32 v48, v53, v68
	v_mul_f32_e32 v74, v54, v49
	v_fmac_f32_e32 v51, v70, v70
	v_add_f32_e32 v50, v52, v50
	v_mul_f32_e32 v52, v69, v69
	v_fma_f32 v49, v54, v49, v71
	v_add_f32_e32 v51, v51, v60
	v_fmac_f32_e32 v52, v48, v48
	v_add_f32_e32 v49, v49, v50
	v_mul_f32_e32 v50, v71, v71
	v_add_f32_e32 v51, v52, v51
	v_fmac_f32_e32 v50, v74, v74
	v_add_f32_e32 v50, v50, v51
	v_fma_f32 v51, v55, v72, v73
	v_mul_f32_e32 v75, v55, v72
	v_add_f32_e32 v49, v51, v49
	v_mul_f32_e32 v51, v73, v73
	v_fmac_f32_e32 v51, v75, v75
	v_add_f32_e32 v50, v51, v50
	v_mov_b32_e32 v53, v49
	s_nop 1
	v_permlane16_swap_b32_e32 v53, v49
	v_mov_b32_e32 v51, v50
	s_nop 1
	v_permlane16_swap_b32_e32 v51, v50
	v_lshl_add_u64 v[66:67], s[70:71], 0, v[66:67]
	v_lshl_add_u64 v[66:67], v[160:161], 1, v[66:67]
	global_store_dwordx4 v[66:67], v[56:59], off nt
	v_cvt_pk_bf16_f32 v52, v70, v48
	s_waitcnt lgkmcnt(0)
	v_add_f32_e32 v48, v49, v53
	v_add_f32_e32 v50, v50, v51
	v_mov_b32_e32 v49, v48
	s_nop 1
	v_permlane32_swap_b32_e32 v49, v48
	v_mov_b32_e32 v51, v50
	s_nop 1
	v_permlane32_swap_b32_e32 v51, v50
	v_cvt_pk_bf16_f32 v53, v74, v75
	v_cvt_pk_bf16_f32 v54, v63, v69
	v_cvt_pk_bf16_f32 v55, v71, v73
	global_store_dwordx4 v[66:67], v[52:55], off offset:256 nt
	s_and_saveexec_b64 s[6:7], s[58:59]
	s_cbranch_execz .LBB0_585
	s_waitcnt lgkmcnt(0)
	v_add_f32_e32 v50, v50, v51
	v_add_f32_e32 v51, v48, v49
	s_lshl_b32 s4, s95, 2
	v_lshlrev_b64 v[48:49], 7, v[64:65]
	s_add_i32 s38, s4, -16
	v_lshl_add_u64 v[48:49], s[72:73], 0, v[48:49]
	v_lshl_add_u64 v[48:49], s[38:39], 2, v[48:49]
	s_lshl_b32 s38, s8, 2
	v_lshl_add_u64 v[48:49], v[48:49], 0, s[38:39]
	global_store_dword v[48:49], v51, off
	global_store_dword v[48:49], v50, off offset:64

.LBB0_589:
	s_waitcnt lgkmcnt(0)
	v_pk_mul_f32 v[44:45], v[44:45], v[52:53] op_sel_hi:[1,0]
	v_lshlrev_b64 v[50:51], 12, v[48:49]
	v_mul_f32_e32 v53, v44, v44
	v_fmamk_f32 v53, v53, 0xbdd2d3e7, v152
	v_mul_f32_e32 v53, v44, v53
	v_exp_f32_e32 v53, v53
	v_mul_f32_e32 v55, v45, v45
	v_fmamk_f32 v55, v55, 0xbdd2d3e7, v152
	v_mul_f32_e32 v55, v45, v55
	v_pk_mul_f32 v[40:41], v[40:41], v[52:53] op_sel_hi:[1,0]
	v_pk_mul_f32 v[46:47], v[46:47], v[52:53] op_sel_hi:[1,0]
	v_mul_f32_e32 v56, v41, v41
	v_fmamk_f32 v56, v56, 0xbdd2d3e7, v152
	v_mul_f32_e32 v56, v41, v56
	v_pk_mul_f32 v[42:43], v[42:43], v[52:53] op_sel_hi:[1,0]
	v_exp_f32_e32 v56, v56
	v_mul_f32_e32 v58, v46, v46
	v_mul_f32_e32 v59, v42, v42
	v_fmamk_f32 v58, v58, 0xbdd2d3e7, v152
	v_fmamk_f32 v59, v59, 0xbdd2d3e7, v152
	v_mul_f32_e32 v54, v40, v40
	v_mul_f32_e32 v58, v46, v58
	v_mul_f32_e32 v59, v42, v59
	v_fmamk_f32 v54, v54, 0xbdd2d3e7, v152
	v_mul_f32_e32 v54, v40, v54
	v_add_f32_e32 v56, 1.0, v56
	v_rcp_f32_e32 v56, v56
	v_exp_f32_e32 v58, v58
	v_exp_f32_e32 v59, v59
	v_exp_f32_e32 v54, v54
	v_mul_f32_e32 v60, v43, v43
	v_exp_f32_e32 v55, v55
	v_mul_f32_e32 v56, v41, v56
	v_add_f32_e32 v41, 1.0, v58
	v_add_f32_e32 v58, 1.0, v59
	v_mul_f32_e32 v59, v47, v47
	v_fmamk_f32 v60, v60, 0xbdd2d3e7, v152
	v_fmamk_f32 v59, v59, 0xbdd2d3e7, v152
	v_mul_f32_e32 v60, v43, v60
	v_add_f32_e32 v54, 1.0, v54
	v_mul_f32_e32 v59, v47, v59
	v_add_f32_e32 v53, 1.0, v53
	v_rcp_f32_e32 v54, v54
	v_rcp_f32_e32 v53, v53
	v_add_f32_e32 v55, 1.0, v55
	v_exp_f32_e32 v60, v60
	v_rcp_f32_e32 v55, v55
	v_exp_f32_e32 v59, v59
	v_rcp_f32_e32 v58, v58
	v_mul_f32_e32 v54, v40, v54
	v_rcp_f32_e32 v41, v41
	v_mul_f32_e32 v57, v44, v53
	v_add_f32_e32 v60, 1.0, v60
	v_fma_f32 v44, v44, v53, v54
	v_mul_f32_e32 v40, v45, v55
	v_add_f32_e32 v59, 1.0, v59
	v_rcp_f32_e32 v60, v60
	v_add_f32_e32 v44, 0, v44
	v_mul_f32_e32 v53, v54, v54
	v_fma_f32 v45, v45, v55, v56
	v_rcp_f32_e32 v59, v59
	v_mul_f32_e32 v58, v42, v58
	v_fmac_f32_e32 v53, v57, v57
	v_add_f32_e32 v44, v45, v44
	v_mul_f32_e32 v45, v56, v56
	v_mul_f32_e32 v61, v46, v41
	v_fmac_f32_e32 v45, v40, v40
	v_fma_f32 v41, v46, v41, v58
	v_pk_mul_f32 v[32:33], v[32:33], v[52:53] op_sel_hi:[1,0]
	v_add_f32_e32 v45, v53, v45
	v_add_f32_e32 v41, v41, v44
	v_mul_f32_e32 v44, v58, v58
	v_pk_mul_f32 v[36:37], v[36:37], v[52:53] op_sel_hi:[1,0]
	v_pk_mul_f32 v[38:39], v[38:39], v[52:53] op_sel_hi:[1,0]
	v_pk_mul_f32 v[34:35], v[34:35], v[52:53] op_sel_hi:[1,0]
	v_mul_f32_e32 v53, v33, v33
	v_mul_f32_e32 v43, v43, v60
	v_fmac_f32_e32 v44, v61, v61
	v_fmamk_f32 v53, v53, 0xbdd2d3e7, v152
	v_add_f32_e32 v44, v44, v45
	v_fma_f32 v45, v47, v59, v43
	v_mul_f32_e32 v53, v33, v53
	v_mul_f32_e32 v42, v47, v59
	v_add_f32_e32 v45, v45, v41
	v_mul_f32_e32 v41, v43, v43
	v_fmac_f32_e32 v41, v42, v42
	v_add_f32_e32 v44, v41, v44
	v_cvt_pk_bf16_f32 v40, v57, v40
	v_cvt_pk_bf16_f32 v41, v61, v42
	v_cvt_pk_bf16_f32 v42, v54, v56
	v_exp_f32_e32 v53, v53
	v_mul_f32_e32 v55, v38, v38
	v_mul_f32_e32 v56, v34, v34
	v_fmamk_f32 v55, v55, 0xbdd2d3e7, v152
	v_fmamk_f32 v56, v56, 0xbdd2d3e7, v152
	v_mul_f32_e32 v55, v38, v55
	v_mul_f32_e32 v56, v34, v56
	v_mul_f32_e32 v47, v32, v32
	v_mul_f32_e32 v46, v36, v36
	v_fmamk_f32 v47, v47, 0xbdd2d3e7, v152
	v_add_f32_e32 v53, 1.0, v53
	v_fmamk_f32 v46, v46, 0xbdd2d3e7, v152
	v_mul_f32_e32 v47, v32, v47
	v_mul_f32_e32 v52, v37, v37
	v_rcp_f32_e32 v53, v53
	v_exp_f32_e32 v55, v55
	v_exp_f32_e32 v56, v56
	v_mul_f32_e32 v57, v35, v35
	v_mul_f32_e32 v46, v36, v46
	v_fmamk_f32 v52, v52, 0xbdd2d3e7, v152
	v_fmamk_f32 v57, v57, 0xbdd2d3e7, v152
	v_mul_f32_e32 v52, v37, v52
	v_mul_f32_e32 v57, v35, v57
	v_exp_f32_e32 v47, v47
	v_exp_f32_e32 v46, v46
	v_mul_f32_e32 v53, v33, v53
	v_add_f32_e32 v33, 1.0, v55
	v_add_f32_e32 v55, 1.0, v56
	v_mul_f32_e32 v56, v39, v39
	v_exp_f32_e32 v52, v52
	v_fmamk_f32 v56, v56, 0xbdd2d3e7, v152
	v_exp_f32_e32 v57, v57
	v_mul_f32_e32 v56, v39, v56
	v_add_f32_e32 v47, 1.0, v47
	v_add_f32_e32 v46, 1.0, v46
	v_rcp_f32_e32 v47, v47
	v_rcp_f32_e32 v46, v46
	v_add_f32_e32 v52, 1.0, v52
	v_exp_f32_e32 v56, v56
	v_rcp_f32_e32 v55, v55
	v_add_f32_e32 v57, 1.0, v57
	v_rcp_f32_e32 v52, v52
	v_rcp_f32_e32 v57, v57
	v_rcp_f32_e32 v33, v33
	v_mul_f32_e32 v47, v32, v47
	v_add_f32_e32 v56, 1.0, v56
	v_mul_f32_e32 v55, v34, v55
	v_fma_f32 v34, v36, v46, v47
	v_mul_f32_e32 v54, v36, v46
	v_rcp_f32_e32 v56, v56
	v_mul_f32_e32 v57, v35, v57
	v_add_f32_e32 v34, v34, v45
	v_mul_f32_e32 v35, v47, v47
	v_fma_f32 v36, v37, v52, v53
	v_cvt_pk_bf16_f32 v43, v58, v43
	v_mul_f32_e32 v32, v37, v52
	v_mul_f32_e32 v58, v38, v33
	v_fmac_f32_e32 v35, v54, v54
	v_add_f32_e32 v34, v36, v34
	v_mul_f32_e32 v36, v53, v53
	v_fma_f32 v33, v38, v33, v55
	v_add_f32_e32 v35, v35, v44
	v_fmac_f32_e32 v36, v32, v32
	v_add_f32_e32 v33, v33, v34
	v_mul_f32_e32 v34, v55, v55
	v_add_f32_e32 v35, v36, v35
	v_fmac_f32_e32 v34, v58, v58
	v_add_f32_e32 v34, v34, v35
	v_fma_f32 v35, v39, v56, v57
	v_mul_f32_e32 v59, v39, v56
	v_add_f32_e32 v33, v35, v33
	v_mul_f32_e32 v35, v57, v57
	v_fmac_f32_e32 v35, v59, v59
	v_add_f32_e32 v34, v35, v34
	v_mov_b32_e32 v37, v33
	s_nop 1
	v_permlane16_swap_b32_e32 v37, v33
	v_mov_b32_e32 v35, v34
	s_nop 1
	v_permlane16_swap_b32_e32 v35, v34
	v_lshl_add_u64 v[50:51], s[70:71], 0, v[50:51]
	v_lshl_add_u64 v[50:51], v[160:161], 1, v[50:51]
	global_store_dwordx4 v[50:51], v[40:43], off nt
	v_cvt_pk_bf16_f32 v36, v54, v32
	s_waitcnt lgkmcnt(0)
	v_add_f32_e32 v32, v33, v37
	v_add_f32_e32 v34, v34, v35
	v_mov_b32_e32 v33, v32
	s_nop 1
	v_permlane32_swap_b32_e32 v33, v32
	v_mov_b32_e32 v35, v34
	s_nop 1
	v_permlane32_swap_b32_e32 v35, v34
	v_cvt_pk_bf16_f32 v37, v58, v59
	v_cvt_pk_bf16_f32 v38, v47, v53
	v_cvt_pk_bf16_f32 v39, v55, v57
	global_store_dwordx4 v[50:51], v[36:39], off offset:256 nt
	s_and_saveexec_b64 s[6:7], s[58:59]
	s_cbranch_execz .LBB0_591
	s_waitcnt lgkmcnt(0)
	v_add_f32_e32 v34, v34, v35
	v_add_f32_e32 v35, v32, v33
	s_lshl_b32 s4, s95, 2
	v_lshlrev_b64 v[32:33], 7, v[48:49]
	s_add_i32 s38, s4, -16
	v_lshl_add_u64 v[32:33], s[72:73], 0, v[32:33]
	v_lshl_add_u64 v[32:33], s[38:39], 2, v[32:33]
	s_lshl_b32 s38, s8, 2
	v_lshl_add_u64 v[32:33], v[32:33], 0, s[38:39]
	global_store_dword v[32:33], v35, off
	global_store_dword v[32:33], v34, off offset:64

.LBB0_595:
	s_waitcnt lgkmcnt(0)
	v_pk_mul_f32 v[28:29], v[28:29], v[36:37] op_sel_hi:[1,0]
	v_lshlrev_b64 v[34:35], 12, v[32:33]
	v_mul_f32_e32 v37, v28, v28
	v_fmamk_f32 v37, v37, 0xbdd2d3e7, v152
	v_mul_f32_e32 v37, v28, v37
	v_exp_f32_e32 v37, v37
	v_mul_f32_e32 v39, v29, v29
	v_fmamk_f32 v39, v39, 0xbdd2d3e7, v152
	v_mul_f32_e32 v39, v29, v39
	v_pk_mul_f32 v[24:25], v[24:25], v[36:37] op_sel_hi:[1,0]
	v_pk_mul_f32 v[30:31], v[30:31], v[36:37] op_sel_hi:[1,0]
	v_mul_f32_e32 v40, v25, v25
	v_fmamk_f32 v40, v40, 0xbdd2d3e7, v152
	v_mul_f32_e32 v40, v25, v40
	v_pk_mul_f32 v[26:27], v[26:27], v[36:37] op_sel_hi:[1,0]
	v_exp_f32_e32 v40, v40
	v_mul_f32_e32 v42, v30, v30
	v_mul_f32_e32 v43, v26, v26
	v_fmamk_f32 v42, v42, 0xbdd2d3e7, v152
	v_fmamk_f32 v43, v43, 0xbdd2d3e7, v152
	v_mul_f32_e32 v38, v24, v24
	v_mul_f32_e32 v42, v30, v42
	v_mul_f32_e32 v43, v26, v43
	v_fmamk_f32 v38, v38, 0xbdd2d3e7, v152
	v_mul_f32_e32 v38, v24, v38
	v_add_f32_e32 v40, 1.0, v40
	v_rcp_f32_e32 v40, v40
	v_exp_f32_e32 v42, v42
	v_exp_f32_e32 v43, v43
	v_exp_f32_e32 v38, v38
	v_mul_f32_e32 v44, v27, v27
	v_exp_f32_e32 v39, v39
	v_mul_f32_e32 v40, v25, v40
	v_add_f32_e32 v25, 1.0, v42
	v_add_f32_e32 v42, 1.0, v43
	v_mul_f32_e32 v43, v31, v31
	v_fmamk_f32 v44, v44, 0xbdd2d3e7, v152
	v_fmamk_f32 v43, v43, 0xbdd2d3e7, v152
	v_mul_f32_e32 v44, v27, v44
	v_add_f32_e32 v38, 1.0, v38
	v_mul_f32_e32 v43, v31, v43
	v_add_f32_e32 v37, 1.0, v37
	v_rcp_f32_e32 v38, v38
	v_rcp_f32_e32 v37, v37
	v_add_f32_e32 v39, 1.0, v39
	v_exp_f32_e32 v44, v44
	v_rcp_f32_e32 v39, v39
	v_exp_f32_e32 v43, v43
	v_rcp_f32_e32 v42, v42
	v_mul_f32_e32 v38, v24, v38
	v_rcp_f32_e32 v25, v25
	v_mul_f32_e32 v41, v28, v37
	v_add_f32_e32 v44, 1.0, v44
	v_fma_f32 v28, v28, v37, v38
	v_mul_f32_e32 v24, v29, v39
	v_add_f32_e32 v43, 1.0, v43
	v_rcp_f32_e32 v44, v44
	v_add_f32_e32 v28, 0, v28
	v_mul_f32_e32 v37, v38, v38
	v_fma_f32 v29, v29, v39, v40
	v_rcp_f32_e32 v43, v43
	v_mul_f32_e32 v42, v26, v42
	v_fmac_f32_e32 v37, v41, v41
	v_add_f32_e32 v28, v29, v28
	v_mul_f32_e32 v29, v40, v40
	v_mul_f32_e32 v45, v30, v25
	v_fmac_f32_e32 v29, v24, v24
	v_fma_f32 v25, v30, v25, v42
	v_pk_mul_f32 v[16:17], v[16:17], v[36:37] op_sel_hi:[1,0]
	v_add_f32_e32 v29, v37, v29
	v_add_f32_e32 v25, v25, v28
	v_mul_f32_e32 v28, v42, v42
	v_pk_mul_f32 v[20:21], v[20:21], v[36:37] op_sel_hi:[1,0]
	v_pk_mul_f32 v[22:23], v[22:23], v[36:37] op_sel_hi:[1,0]
	v_pk_mul_f32 v[18:19], v[18:19], v[36:37] op_sel_hi:[1,0]
	v_mul_f32_e32 v37, v17, v17
	v_mul_f32_e32 v27, v27, v44
	v_fmac_f32_e32 v28, v45, v45
	v_fmamk_f32 v37, v37, 0xbdd2d3e7, v152
	v_add_f32_e32 v28, v28, v29
	v_fma_f32 v29, v31, v43, v27
	v_mul_f32_e32 v37, v17, v37
	v_mul_f32_e32 v26, v31, v43
	v_add_f32_e32 v29, v29, v25
	v_mul_f32_e32 v25, v27, v27
	v_fmac_f32_e32 v25, v26, v26
	v_add_f32_e32 v28, v25, v28
	v_cvt_pk_bf16_f32 v24, v41, v24
	v_cvt_pk_bf16_f32 v25, v45, v26
	v_cvt_pk_bf16_f32 v26, v38, v40
	v_exp_f32_e32 v37, v37
	v_mul_f32_e32 v39, v22, v22
	v_mul_f32_e32 v40, v18, v18
	v_fmamk_f32 v39, v39, 0xbdd2d3e7, v152
	v_fmamk_f32 v40, v40, 0xbdd2d3e7, v152
	v_mul_f32_e32 v39, v22, v39
	v_mul_f32_e32 v40, v18, v40
	v_mul_f32_e32 v31, v16, v16
	v_mul_f32_e32 v30, v20, v20
	v_fmamk_f32 v31, v31, 0xbdd2d3e7, v152
	v_add_f32_e32 v37, 1.0, v37
	v_fmamk_f32 v30, v30, 0xbdd2d3e7, v152
	v_mul_f32_e32 v31, v16, v31
	v_mul_f32_e32 v36, v21, v21
	v_rcp_f32_e32 v37, v37
	v_exp_f32_e32 v39, v39
	v_exp_f32_e32 v40, v40
	v_mul_f32_e32 v41, v19, v19
	v_mul_f32_e32 v30, v20, v30
	v_fmamk_f32 v36, v36, 0xbdd2d3e7, v152
	v_fmamk_f32 v41, v41, 0xbdd2d3e7, v152
	v_mul_f32_e32 v36, v21, v36
	v_mul_f32_e32 v41, v19, v41
	v_exp_f32_e32 v31, v31
	v_exp_f32_e32 v30, v30
	v_mul_f32_e32 v37, v17, v37
	v_add_f32_e32 v17, 1.0, v39
	v_add_f32_e32 v39, 1.0, v40
	v_mul_f32_e32 v40, v23, v23
	v_exp_f32_e32 v36, v36
	v_fmamk_f32 v40, v40, 0xbdd2d3e7, v152
	v_exp_f32_e32 v41, v41
	v_mul_f32_e32 v40, v23, v40
	v_add_f32_e32 v31, 1.0, v31
	v_add_f32_e32 v30, 1.0, v30
	v_rcp_f32_e32 v31, v31
	v_rcp_f32_e32 v30, v30
	v_add_f32_e32 v36, 1.0, v36
	v_exp_f32_e32 v40, v40
	v_rcp_f32_e32 v39, v39
	v_add_f32_e32 v41, 1.0, v41
	v_rcp_f32_e32 v36, v36
	v_rcp_f32_e32 v41, v41
	v_rcp_f32_e32 v17, v17
	v_mul_f32_e32 v31, v16, v31
	v_add_f32_e32 v40, 1.0, v40
	v_mul_f32_e32 v39, v18, v39
	v_fma_f32 v18, v20, v30, v31
	v_mul_f32_e32 v38, v20, v30
	v_rcp_f32_e32 v40, v40
	v_mul_f32_e32 v41, v19, v41
	v_add_f32_e32 v18, v18, v29
	v_mul_f32_e32 v19, v31, v31
	v_fma_f32 v20, v21, v36, v37
	v_cvt_pk_bf16_f32 v27, v42, v27
	v_mul_f32_e32 v16, v21, v36
	v_mul_f32_e32 v42, v22, v17
	v_fmac_f32_e32 v19, v38, v38
	v_add_f32_e32 v18, v20, v18
	v_mul_f32_e32 v20, v37, v37
	v_fma_f32 v17, v22, v17, v39
	v_add_f32_e32 v19, v19, v28
	v_fmac_f32_e32 v20, v16, v16
	v_add_f32_e32 v17, v17, v18
	v_mul_f32_e32 v18, v39, v39
	v_add_f32_e32 v19, v20, v19
	v_fmac_f32_e32 v18, v42, v42
	v_add_f32_e32 v18, v18, v19
	v_fma_f32 v19, v23, v40, v41
	v_mul_f32_e32 v43, v23, v40
	v_add_f32_e32 v17, v19, v17
	v_mul_f32_e32 v19, v41, v41
	v_fmac_f32_e32 v19, v43, v43
	v_add_f32_e32 v18, v19, v18
	v_mov_b32_e32 v21, v17
	s_nop 1
	v_permlane16_swap_b32_e32 v21, v17
	v_mov_b32_e32 v19, v18
	s_nop 1
	v_permlane16_swap_b32_e32 v19, v18
	v_lshl_add_u64 v[34:35], s[70:71], 0, v[34:35]
	v_lshl_add_u64 v[34:35], v[160:161], 1, v[34:35]
	global_store_dwordx4 v[34:35], v[24:27], off nt
	v_cvt_pk_bf16_f32 v20, v38, v16
	s_waitcnt lgkmcnt(0)
	v_add_f32_e32 v16, v17, v21
	v_add_f32_e32 v18, v18, v19
	v_mov_b32_e32 v17, v16
	s_nop 1
	v_permlane32_swap_b32_e32 v17, v16
	v_mov_b32_e32 v19, v18
	s_nop 1
	v_permlane32_swap_b32_e32 v19, v18
	v_cvt_pk_bf16_f32 v21, v42, v43
	v_cvt_pk_bf16_f32 v22, v31, v37
	v_cvt_pk_bf16_f32 v23, v39, v41
	global_store_dwordx4 v[34:35], v[20:23], off offset:256 nt
	s_and_saveexec_b64 s[6:7], s[58:59]
	s_cbranch_execz .LBB0_597
	s_waitcnt lgkmcnt(0)
	v_add_f32_e32 v18, v18, v19
	v_add_f32_e32 v19, v16, v17
	s_lshl_b32 s4, s95, 2
	v_lshlrev_b64 v[16:17], 7, v[32:33]
	s_add_i32 s38, s4, -16
	v_lshl_add_u64 v[16:17], s[72:73], 0, v[16:17]
	v_lshl_add_u64 v[16:17], s[38:39], 2, v[16:17]
	s_lshl_b32 s38, s8, 2
	v_lshl_add_u64 v[16:17], v[16:17], 0, s[38:39]
	global_store_dword v[16:17], v19, off
	global_store_dword v[16:17], v18, off offset:64

.LBB0_601:
	s_waitcnt lgkmcnt(0)
	v_pk_mul_f32 v[12:13], v[12:13], v[20:21] op_sel_hi:[1,0]
	v_lshlrev_b64 v[18:19], 12, v[16:17]
	v_mul_f32_e32 v21, v12, v12
	v_fmamk_f32 v21, v21, 0xbdd2d3e7, v152
	v_mul_f32_e32 v21, v12, v21
	v_exp_f32_e32 v21, v21
	v_mul_f32_e32 v23, v13, v13
	v_fmamk_f32 v23, v23, 0xbdd2d3e7, v152
	v_mul_f32_e32 v23, v13, v23
	v_pk_mul_f32 v[8:9], v[8:9], v[20:21] op_sel_hi:[1,0]
	v_pk_mul_f32 v[14:15], v[14:15], v[20:21] op_sel_hi:[1,0]
	v_mul_f32_e32 v24, v9, v9
	v_fmamk_f32 v24, v24, 0xbdd2d3e7, v152
	v_mul_f32_e32 v24, v9, v24
	v_pk_mul_f32 v[10:11], v[10:11], v[20:21] op_sel_hi:[1,0]
	v_exp_f32_e32 v24, v24
	v_mul_f32_e32 v26, v14, v14
	v_mul_f32_e32 v27, v10, v10
	v_fmamk_f32 v26, v26, 0xbdd2d3e7, v152
	v_fmamk_f32 v27, v27, 0xbdd2d3e7, v152
	v_mul_f32_e32 v22, v8, v8
	v_mul_f32_e32 v26, v14, v26
	v_mul_f32_e32 v27, v10, v27
	v_fmamk_f32 v22, v22, 0xbdd2d3e7, v152
	v_mul_f32_e32 v22, v8, v22
	v_add_f32_e32 v24, 1.0, v24
	v_rcp_f32_e32 v24, v24
	v_exp_f32_e32 v26, v26
	v_exp_f32_e32 v27, v27
	v_exp_f32_e32 v22, v22
	v_mul_f32_e32 v28, v11, v11
	v_exp_f32_e32 v23, v23
	v_mul_f32_e32 v24, v9, v24
	v_add_f32_e32 v9, 1.0, v26
	v_add_f32_e32 v26, 1.0, v27
	v_mul_f32_e32 v27, v15, v15
	v_fmamk_f32 v28, v28, 0xbdd2d3e7, v152
	v_fmamk_f32 v27, v27, 0xbdd2d3e7, v152
	v_mul_f32_e32 v28, v11, v28
	v_add_f32_e32 v22, 1.0, v22
	v_mul_f32_e32 v27, v15, v27
	v_add_f32_e32 v21, 1.0, v21
	v_rcp_f32_e32 v22, v22
	v_rcp_f32_e32 v21, v21
	v_add_f32_e32 v23, 1.0, v23
	v_exp_f32_e32 v28, v28
	v_rcp_f32_e32 v23, v23
	v_exp_f32_e32 v27, v27
	v_rcp_f32_e32 v26, v26
	v_mul_f32_e32 v22, v8, v22
	v_rcp_f32_e32 v9, v9
	v_mul_f32_e32 v25, v12, v21
	v_add_f32_e32 v28, 1.0, v28
	v_fma_f32 v12, v12, v21, v22
	v_mul_f32_e32 v8, v13, v23
	v_add_f32_e32 v27, 1.0, v27
	v_rcp_f32_e32 v28, v28
	v_add_f32_e32 v12, 0, v12
	v_mul_f32_e32 v21, v22, v22
	v_fma_f32 v13, v13, v23, v24
	v_rcp_f32_e32 v27, v27
	v_mul_f32_e32 v26, v10, v26
	v_fmac_f32_e32 v21, v25, v25
	v_add_f32_e32 v12, v13, v12
	v_mul_f32_e32 v13, v24, v24
	v_mul_f32_e32 v29, v14, v9
	v_fmac_f32_e32 v13, v8, v8
	v_fma_f32 v9, v14, v9, v26
	v_pk_mul_f32 v[0:1], v[0:1], v[20:21] op_sel_hi:[1,0]
	v_add_f32_e32 v13, v21, v13
	v_add_f32_e32 v9, v9, v12
	v_mul_f32_e32 v12, v26, v26
	v_pk_mul_f32 v[4:5], v[4:5], v[20:21] op_sel_hi:[1,0]
	v_pk_mul_f32 v[6:7], v[6:7], v[20:21] op_sel_hi:[1,0]
	v_pk_mul_f32 v[2:3], v[2:3], v[20:21] op_sel_hi:[1,0]
	v_mul_f32_e32 v21, v1, v1
	v_mul_f32_e32 v11, v11, v28
	v_fmac_f32_e32 v12, v29, v29
	v_fmamk_f32 v21, v21, 0xbdd2d3e7, v152
	v_add_f32_e32 v12, v12, v13
	v_fma_f32 v13, v15, v27, v11
	v_mul_f32_e32 v21, v1, v21
	v_mul_f32_e32 v10, v15, v27
	v_add_f32_e32 v13, v13, v9
	v_mul_f32_e32 v9, v11, v11
	v_fmac_f32_e32 v9, v10, v10
	v_add_f32_e32 v12, v9, v12
	v_cvt_pk_bf16_f32 v8, v25, v8
	v_cvt_pk_bf16_f32 v9, v29, v10
	v_cvt_pk_bf16_f32 v10, v22, v24
	v_exp_f32_e32 v21, v21
	v_mul_f32_e32 v23, v6, v6
	v_mul_f32_e32 v24, v2, v2
	v_fmamk_f32 v23, v23, 0xbdd2d3e7, v152
	v_fmamk_f32 v24, v24, 0xbdd2d3e7, v152
	v_mul_f32_e32 v23, v6, v23
	v_mul_f32_e32 v24, v2, v24
	v_mul_f32_e32 v15, v0, v0
	v_mul_f32_e32 v14, v4, v4
	v_fmamk_f32 v15, v15, 0xbdd2d3e7, v152
	v_add_f32_e32 v21, 1.0, v21
	v_fmamk_f32 v14, v14, 0xbdd2d3e7, v152
	v_mul_f32_e32 v15, v0, v15
	v_mul_f32_e32 v20, v5, v5
	v_rcp_f32_e32 v21, v21
	v_exp_f32_e32 v23, v23
	v_exp_f32_e32 v24, v24
	v_mul_f32_e32 v25, v3, v3
	v_mul_f32_e32 v14, v4, v14
	v_fmamk_f32 v20, v20, 0xbdd2d3e7, v152
	v_fmamk_f32 v25, v25, 0xbdd2d3e7, v152
	v_mul_f32_e32 v20, v5, v20
	v_mul_f32_e32 v25, v3, v25
	v_exp_f32_e32 v15, v15
	v_exp_f32_e32 v14, v14
	v_mul_f32_e32 v21, v1, v21
	v_add_f32_e32 v1, 1.0, v23
	v_add_f32_e32 v23, 1.0, v24
	v_mul_f32_e32 v24, v7, v7
	v_exp_f32_e32 v20, v20
	v_fmamk_f32 v24, v24, 0xbdd2d3e7, v152
	v_exp_f32_e32 v25, v25
	v_mul_f32_e32 v24, v7, v24
	v_add_f32_e32 v15, 1.0, v15
	v_add_f32_e32 v14, 1.0, v14
	v_rcp_f32_e32 v15, v15
	v_rcp_f32_e32 v14, v14
	v_add_f32_e32 v20, 1.0, v20
	v_exp_f32_e32 v24, v24
	v_rcp_f32_e32 v23, v23
	v_add_f32_e32 v25, 1.0, v25
	v_rcp_f32_e32 v20, v20
	v_rcp_f32_e32 v25, v25
	v_rcp_f32_e32 v1, v1
	v_mul_f32_e32 v15, v0, v15
	v_add_f32_e32 v24, 1.0, v24
	v_mul_f32_e32 v23, v2, v23
	v_fma_f32 v2, v4, v14, v15
	v_mul_f32_e32 v22, v4, v14
	v_rcp_f32_e32 v24, v24
	v_mul_f32_e32 v25, v3, v25
	v_add_f32_e32 v2, v2, v13
	v_mul_f32_e32 v3, v15, v15
	v_fma_f32 v4, v5, v20, v21
	v_cvt_pk_bf16_f32 v11, v26, v11
	v_mul_f32_e32 v0, v5, v20
	v_mul_f32_e32 v26, v6, v1
	v_fmac_f32_e32 v3, v22, v22
	v_add_f32_e32 v2, v4, v2
	v_mul_f32_e32 v4, v21, v21
	v_fma_f32 v1, v6, v1, v23
	v_add_f32_e32 v3, v3, v12
	v_fmac_f32_e32 v4, v0, v0
	v_add_f32_e32 v1, v1, v2
	v_mul_f32_e32 v2, v23, v23
	v_add_f32_e32 v3, v4, v3
	v_fmac_f32_e32 v2, v26, v26
	v_add_f32_e32 v2, v2, v3
	v_fma_f32 v3, v7, v24, v25
	v_mul_f32_e32 v27, v7, v24
	v_add_f32_e32 v1, v3, v1
	v_mul_f32_e32 v3, v25, v25
	v_fmac_f32_e32 v3, v27, v27
	v_add_f32_e32 v2, v3, v2
	v_mov_b32_e32 v5, v1
	s_nop 1
	v_permlane16_swap_b32_e32 v5, v1
	v_mov_b32_e32 v3, v2
	s_nop 1
	v_permlane16_swap_b32_e32 v3, v2
	v_lshl_add_u64 v[18:19], s[70:71], 0, v[18:19]
	v_lshl_add_u64 v[18:19], v[160:161], 1, v[18:19]
	global_store_dwordx4 v[18:19], v[8:11], off nt
	v_cvt_pk_bf16_f32 v4, v22, v0
	s_waitcnt lgkmcnt(0)
	v_add_f32_e32 v0, v1, v5
	v_add_f32_e32 v2, v2, v3
	v_mov_b32_e32 v1, v0
	s_nop 1
	v_permlane32_swap_b32_e32 v1, v0
	v_mov_b32_e32 v3, v2
	s_nop 1
	v_permlane32_swap_b32_e32 v3, v2
	v_cvt_pk_bf16_f32 v5, v26, v27
	v_cvt_pk_bf16_f32 v6, v15, v21
	v_cvt_pk_bf16_f32 v7, v23, v25
	global_store_dwordx4 v[18:19], v[4:7], off offset:256 nt
	s_and_saveexec_b64 s[6:7], s[58:59]
	s_cbranch_execz .LBB0_603
	s_waitcnt lgkmcnt(0)
	v_add_f32_e32 v2, v2, v3
	v_add_f32_e32 v3, v0, v1
	s_lshl_b32 s4, s95, 2
	v_lshlrev_b64 v[0:1], 7, v[16:17]
	s_add_i32 s38, s4, -16
	v_lshl_add_u64 v[0:1], s[72:73], 0, v[0:1]
	v_lshl_add_u64 v[0:1], s[38:39], 2, v[0:1]
	s_lshl_b32 s38, s8, 2
	v_lshl_add_u64 v[0:1], v[0:1], 0, s[38:39]
	global_store_dword v[0:1], v3, off
	global_store_dword v[0:1], v2, off offset:64
